# gdn_prep stage A: the 21 row loads per chunk issued back to back into distinct registers with one wait (were serialized load/wait/mask), on top of v9
# speedup vs baseline: 1.0152x; 1.0152x over previous
; __device__ __forceinline__ float bf2f(bf16 v) { return __uint_as_float(((unsigned)v) << 16); }
; __device__ __forceinline__ float siluf_(float x) { return x * sigmoidf_(x); }
; template <int STRIP> __device__ __forceinline__ void ph_gdn_prep_fast(const bf16* __restrict__ proj, const float* __restrict__ small, const float* __restrict__ conv_w, const float* __restrict__ a_log, const float* __restrict__ dt_bias, ...
;     ...
;                 u32x2 xr[3][7];
; #pragma unroll
;                 for (int which = 0; which < 3; ++which)
; #pragma unroll
;                     for (int r = 0; r < 7; ++r) { const bool ok = tb + r >= 0; const bf16* src = proj + (m0 + 4 * ts - (ok ? 3 - r : 0)) * NPROJ + which * 768 + h * 128 + 4 * cg;
;                         xr[which][r] = *(const u32x2*)src; if (!ok) xr[which][r] = (u32x2){0u, 0u}; }
; #pragma unroll
;                 for (int which = 0; which < 3; ++which) {
;                     float xf[7][4];
; #pragma unroll
;                     for (int r = 0; r < 7; ++r) { xf[r][0] = bf2f((bf16)(xr[which][r].x & 0xffff)); xf[r][1] = bf2f((bf16)(xr[which][r].x >> 16)); xf[r][2] = bf2f((bf16)(xr[which][r].y & 0xffff)); xf[r][3] = bf2f((bf16)(xr[which][r].y >> 16)); }
; #pragma unroll
;                     for (int j = 0; j < 4; ++j) { float y[4]; float ss = 0.f;
; #pragma unroll
;                         for (int e = 0; e < 4; ++e) { float v = cw[which][0][e] * xf[j][e]; v += cw[which][1][e] * xf[j + 1][e]; v += cw[which][2][e] * xf[j + 2][e]; v += cw[which][3][e] * xf[j + 3][e]; y[e] = siluf_(v); ss += y[e] * y[e]; }
.LBB0_1256:
	v_cndmask_b32_e64 v2, 0, 1, s[0:1]
	v_cmp_ne_u32_e64 s[4:5], 1, v2
	v_or_b32_e32 v2, s2, v53
	v_lshlrev_b32_e32 v2, 6, v2
	v_add_u32_e32 v84, v2, v56
	v_cmp_lt_i32_e64 s[8:9], 2, v84
	v_lshl_add_u64 v[76:77], v[58:59], 0, v[2:3]
	v_cmp_lt_i32_e64 s[14:15], 1, v84
	v_cndmask_b32_e64 v63, 0, -1, s[8:9]
	v_cndmask_b32_e64 v62, 0, -3, s[8:9]
	v_lshl_add_u64 v[62:63], v[62:63], 0, v[76:77]
	v_mad_u64_u32 v[66:67], s[0:1], v62, s23, v[60:61]
	v_mad_i32_i24 v67, v63, s23, v67
	global_load_dwordx2 v[134:135], v[66:67], off
	v_cmp_lt_i32_e64 s[16:17], 0, v84
	v_mad_u64_u32 v[68:69], s[0:1], v76, s23, v[60:61]
	s_nop 0
	v_cndmask_b32_e64 v2, 0, 1, s[16:17]
	v_sub_co_u32_e32 v2, vcc, v76, v2
	v_mad_u64_u32 v[74:75], s[0:1], v2, s23, v[60:61]
	v_mad_i32_i24 v69, v77, s23, v69
	v_cmp_lt_i32_e64 s[10:11], -1, v84
	v_cmp_lt_i32_e64 s[6:7], -3, v84
	v_cmp_lt_i32_e64 s[12:13], -4, v84
	v_cndmask_b32_e64 v63, 0, -1, s[14:15]
	v_cndmask_b32_e64 v62, 0, -2, s[14:15]
	v_lshl_add_u64 v[62:63], v[62:63], 0, v[76:77]
	v_mad_u64_u32 v[70:71], s[0:1], v62, s23, v[60:61]
	v_mad_i32_i24 v71, v63, s23, v71
	global_load_dwordx2 v[136:137], v[70:71], off
	v_subbrev_co_u32_e32 v62, vcc, 0, v77, vcc
	v_mad_i32_i24 v75, v62, s23, v75
	global_load_dwordx2 v[138:139], v[74:75], off
	v_cmp_lt_i32_e32 vcc, -2, v84
	global_load_dwordx2 v[140:141], v[68:69], off
	s_nop 0
	v_cndmask_b32_e64 v2, 0, 1, vcc
	v_or_b32_e32 v2, v76, v2
	v_mad_u64_u32 v[62:63], s[0:1], v2, s23, v[60:61]
	v_mad_i32_i24 v63, v77, s23, v63
	global_load_dwordx2 v[142:143], v[62:63], off
	v_cndmask_b32_e64 v2, 0, 2, s[6:7]
	v_or_b32_e32 v2, v2, v76
	v_mad_u64_u32 v[64:65], s[0:1], v2, s23, v[60:61]
	v_mad_i32_i24 v65, v77, s23, v65
	global_load_dwordx2 v[144:145], v[64:65], off
	v_cndmask_b32_e64 v2, 0, 3, s[12:13]
	v_or_b32_e32 v2, v2, v76
	v_mad_u64_u32 v[72:73], s[0:1], v2, s23, v[60:61]
	v_mad_i32_i24 v73, v77, s23, v73
	global_load_dwordx2 v[146:147], v[72:73], off
	s_mul_i32 s0, s2, 0x11500
	v_add_u32_e32 v118, s0, v80
	s_mov_b32 s2, 1
	global_load_dwordx2 v[148:149], v[66:67], off offset:1536
	global_load_dwordx2 v[150:151], v[70:71], off offset:1536
	global_load_dwordx2 v[152:153], v[74:75], off offset:1536
	global_load_dwordx2 v[154:155], v[68:69], off offset:1536
	global_load_dwordx2 v[156:157], v[62:63], off offset:1536
	s_nop 0
	global_load_dwordx2 v[158:159], v[66:67], off offset:3072
	global_load_dwordx2 v[160:161], v[70:71], off offset:3072
	global_load_dwordx2 v[162:163], v[64:65], off offset:1536
	global_load_dwordx2 v[164:165], v[74:75], off offset:3072
	global_load_dwordx2 v[166:167], v[68:69], off offset:3072
	global_load_dwordx2 v[168:169], v[62:63], off offset:3072
	global_load_dwordx2 v[170:171], v[72:73], off offset:1536
	global_load_dwordx2 v[172:173], v[64:65], off offset:3072
	global_load_dwordx2 v[174:175], v[72:73], off offset:3072
	s_waitcnt vmcnt(0)
	v_cndmask_b32_e64 v119, 0, v134, s[8:9]
	v_cndmask_b32_e64 v122, 0, v135, s[8:9]
	v_cndmask_b32_e64 v120, 0, v136, s[14:15]
	v_cndmask_b32_e64 v124, 0, v137, s[14:15]
	v_cndmask_b32_e64 v121, 0, v138, s[16:17]
	v_cndmask_b32_e64 v125, 0, v139, s[16:17]
	v_cndmask_b32_e64 v87, 0, v140, s[10:11]
	v_cndmask_b32_e64 v123, 0, v141, s[10:11]
	v_cndmask_b32_e32 v116, 0, v142, vcc
	v_cndmask_b32_e32 v117, 0, v143, vcc
	v_cndmask_b32_e64 v113, 0, v144, s[6:7]
	v_cndmask_b32_e64 v115, 0, v145, s[6:7]
	v_cndmask_b32_e64 v2, 0, v146, s[12:13]
	v_cndmask_b32_e64 v114, 0, v147, s[12:13]
	v_cndmask_b32_e64 v106, 0, v148, s[8:9]
	v_cndmask_b32_e64 v110, 0, v149, s[8:9]
	v_cndmask_b32_e64 v107, 0, v150, s[14:15]
	v_cndmask_b32_e64 v111, 0, v151, s[14:15]
	v_cndmask_b32_e64 v108, 0, v152, s[16:17]
	v_cndmask_b32_e64 v112, 0, v153, s[16:17]
	v_cndmask_b32_e64 v105, 0, v154, s[10:11]
	v_cndmask_b32_e64 v109, 0, v155, s[10:11]
	v_cndmask_b32_e32 v103, 0, v156, vcc
	v_cndmask_b32_e32 v104, 0, v157, vcc
	v_cndmask_b32_e64 v88, 0, v158, s[8:9]
	v_cndmask_b32_e64 v95, 0, v159, s[8:9]
	v_cndmask_b32_e64 v89, 0, v160, s[14:15]
	v_cndmask_b32_e64 v96, 0, v161, s[14:15]
	v_cndmask_b32_e64 v94, 0, v164, s[16:17]
	v_cndmask_b32_e64 v98, 0, v165, s[16:17]
	v_and_b32_e32 v69, 0xffff0000, v124
	v_cndmask_b32_e64 v101, 0, v162, s[6:7]
	v_cndmask_b32_e64 v102, 0, v163, s[6:7]
	v_lshlrev_b32_e32 v68, 16, v124
	v_pk_mul_f32 v[70:71], v[6:7], v[68:69]
	v_cndmask_b32_e64 v91, 0, v166, s[10:11]
	v_cndmask_b32_e64 v97, 0, v167, s[10:11]
	v_cndmask_b32_e32 v92, 0, v168, vcc
	v_cndmask_b32_e32 v93, 0, v169, vcc
	v_and_b32_e32 v67, 0xffff0000, v122
	v_lshlrev_b32_e32 v66, 16, v122
	v_pk_fma_f32 v[66:67], v[14:15], v[66:67], v[70:71]
	v_and_b32_e32 v65, 0xffff0000, v123
	v_lshlrev_b32_e32 v64, 16, v123
	v_cndmask_b32_e64 v99, 0, v170, s[12:13]
	v_cndmask_b32_e64 v100, 0, v171, s[12:13]
	v_and_b32_e32 v77, 0xffff0000, v120
	v_and_b32_e32 v123, 0xffff0000, v119
	v_lshlrev_b32_e32 v122, 16, v119
	v_cndmask_b32_e64 v86, 0, v172, s[6:7]
	v_cndmask_b32_e64 v90, 0, v173, s[6:7]
	v_cndmask_b32_e64 v84, 0, v174, s[12:13]
	v_cndmask_b32_e64 v85, 0, v175, s[12:13]
	v_and_b32_e32 v63, 0xffff0000, v125
	v_lshlrev_b32_e32 v62, 16, v125
	v_pk_fma_f32 v[66:67], v[10:11], v[62:63], v[66:67]
	s_nop 0
	v_pk_fma_f32 v[66:67], v[38:39], v[64:65], v[66:67]
	s_nop 0
	v_mul_f32_e32 v70, 0xbfb8aa3b, v66
	v_mul_f32_e32 v71, 0xbfb8aa3b, v67
	v_exp_f32_e32 v70, v70
	v_exp_f32_e32 v71, v71
	s_nop 0
	v_pk_add_f32 v[70:71], v[70:71], 1.0 op_sel_hi:[1,0]
	s_nop 0
	v_div_scale_f32 v72, s[0:1], v71, v71, 1.0
	v_rcp_f32_e32 v73, v72
	s_nop 0
	v_fma_f32 v74, -v72, v73, 1.0
	v_fmac_f32_e32 v73, v74, v73
	v_div_scale_f32 v74, vcc, 1.0, v71, 1.0
	v_mul_f32_e32 v75, v74, v73
	v_fma_f32 v76, -v72, v75, v74
; __device__ __forceinline__ float bf2f(bf16 v) { return __uint_as_float(((unsigned)v) << 16); }
; __device__ __forceinline__ float siluf_(float x) { return x * sigmoidf_(x); }
; __device__ __forceinline__ unsigned cvt2(float lo, float hi) { f32x2 v = {lo, hi}; return __builtin_bit_cast(unsigned, __builtin_convertvector(v, bf16x2_t)); }
; template <int STRIP> __device__ __forceinline__ void ph_gdn_prep_fast(const bf16* __restrict__ proj, const float* __restrict__ small, const float* __restrict__ conv_w, const float* __restrict__ a_log, const float* __restrict__ dt_bias, ...
;     ...
;                 for (int which = 0; which < 3; ++which) {
;                     float xf[7][4];
; #pragma unroll
;                     for (int r = 0; r < 7; ++r) { xf[r][0] = bf2f((bf16)(xr[which][r].x & 0xffff)); xf[r][1] = bf2f((bf16)(xr[which][r].x >> 16)); xf[r][2] = bf2f((bf16)(xr[which][r].y & 0xffff)); xf[r][3] = bf2f((bf16)(xr[which][r].y >> 16)); }
; #pragma unroll
;                     for (int j = 0; j < 4; ++j) { float y[4]; float ss = 0.f;
; #pragma unroll
;                         for (int e = 0; e < 4; ++e) { float v = cw[which][0][e] * xf[j][e]; v += cw[which][1][e] * xf[j + 1][e]; v += cw[which][2][e] * xf[j + 2][e]; v += cw[which][3][e] * xf[j + 3][e]; y[e] = siluf_(v); ss += y[e] * y[e]; }
;                         float r = 1.f;
;                         if (which < 2) { ss = row16_sum(ss); ss += __shfl_xor(ss, 16); r = rsqrtf(ss + NORM_EPS); if (which == 0) r *= 0.08838834764831845f; }
;                         u32x2 o; o.x = cvt2(y[0] * r, y[1] * r); o.y = cvt2(y[2] * r, y[3] * r);
;                         *(u32x2*)(L + which * (64 * GP_STR * 2) + ((4 * ts + j) * GP_STR + 4 * cg) * 2) = o; }
	v_fmac_f32_e32 v75, v76, v73
	v_fma_f32 v72, -v72, v75, v74
	v_div_fmas_f32 v72, v72, v73, v75
	v_div_fixup_f32 v71, v72, v71, 1.0
	v_div_scale_f32 v72, s[0:1], v70, v70, 1.0
	v_rcp_f32_e32 v73, v72
	s_nop 0
	v_fma_f32 v74, -v72, v73, 1.0
	v_fmac_f32_e32 v73, v74, v73
	v_div_scale_f32 v74, vcc, 1.0, v70, 1.0
	v_mul_f32_e32 v75, v74, v73
	v_fma_f32 v76, -v72, v75, v74
	v_fmac_f32_e32 v75, v76, v73
	v_fma_f32 v72, -v72, v75, v74
	v_div_fmas_f32 v72, v72, v73, v75
	v_div_fixup_f32 v70, v72, v70, 1.0
	v_lshlrev_b32_e32 v76, 16, v120
	v_pk_mul_f32 v[70:71], v[66:67], v[70:71]
	v_and_b32_e32 v67, 0xffff0000, v121
	v_lshlrev_b32_e32 v66, 16, v121
	v_pk_mul_f32 v[120:121], v[4:5], v[76:77]
	v_and_b32_e32 v75, 0xffff0000, v87
	v_pk_fma_f32 v[120:121], v[12:13], v[122:123], v[120:121]
	v_lshlrev_b32_e32 v74, 16, v87
	v_pk_fma_f32 v[120:121], v[8:9], v[66:67], v[120:121]
	v_pk_mul_f32 v[72:73], v[70:71], v[70:71]
	v_pk_fma_f32 v[120:121], v[36:37], v[74:75], v[120:121]
	s_nop 0
	v_mul_f32_e32 v87, 0xbfb8aa3b, v120
	v_exp_f32_e32 v122, v87
	v_mul_f32_e32 v87, 0xbfb8aa3b, v121
	v_exp_f32_e32 v123, v87
	s_nop 0
	v_pk_add_f32 v[122:123], v[122:123], 1.0 op_sel_hi:[1,0]
	s_nop 0
	v_div_scale_f32 v87, s[0:1], v123, v123, 1.0
	v_rcp_f32_e32 v119, v87
	s_nop 0
	v_fma_f32 v124, -v87, v119, 1.0
	v_fmac_f32_e32 v119, v124, v119
	v_div_scale_f32 v124, vcc, 1.0, v123, 1.0
	v_mul_f32_e32 v125, v124, v119
	v_fma_f32 v126, -v87, v125, v124
	v_fmac_f32_e32 v125, v126, v119
	v_fma_f32 v87, -v87, v125, v124
	v_div_fmas_f32 v87, v87, v119, v125
	v_div_fixup_f32 v123, v87, v123, 1.0
	v_div_scale_f32 v87, s[0:1], v122, v122, 1.0
	v_rcp_f32_e32 v119, v87
	s_nop 0
	v_fma_f32 v124, -v87, v119, 1.0
	v_fmac_f32_e32 v119, v124, v119
	v_div_scale_f32 v124, vcc, 1.0, v122, 1.0
	v_mul_f32_e32 v125, v124, v119
	v_fma_f32 v126, -v87, v125, v124
	v_fmac_f32_e32 v125, v126, v119
	v_pk_mul_f32 v[126:127], v[6:7], v[62:63]
	v_fma_f32 v87, -v87, v125, v124
	v_pk_fma_f32 v[68:69], v[14:15], v[68:69], v[126:127]
	v_div_fmas_f32 v87, v87, v119, v125
	v_and_b32_e32 v125, 0xffff0000, v117
	v_lshlrev_b32_e32 v124, 16, v117
	v_pk_fma_f32 v[68:69], v[10:11], v[64:65], v[68:69]
	v_div_fixup_f32 v122, v87, v122, 1.0
	v_pk_fma_f32 v[68:69], v[38:39], v[124:125], v[68:69]
	v_pk_mul_f32 v[120:121], v[120:121], v[122:123]
	v_mul_f32_e32 v117, 0xbfb8aa3b, v68
	v_exp_f32_e32 v126, v117
	v_mul_f32_e32 v117, 0xbfb8aa3b, v69
	v_exp_f32_e32 v127, v117
	v_pk_mul_f32 v[122:123], v[120:121], v[120:121]
	v_add_u32_e32 v87, v118, v82
	v_pk_add_f32 v[126:127], v[126:127], 1.0 op_sel_hi:[1,0]
	s_nop 0
	v_div_scale_f32 v117, s[0:1], v127, v127, 1.0
	v_rcp_f32_e32 v119, v117
	s_nop 0
	v_fma_f32 v128, -v117, v119, 1.0
	v_fmac_f32_e32 v119, v128, v119
	v_div_scale_f32 v128, vcc, 1.0, v127, 1.0
	v_mul_f32_e32 v129, v128, v119
	v_fma_f32 v130, -v117, v129, v128
	v_fmac_f32_e32 v129, v130, v119
	v_fma_f32 v117, -v117, v129, v128
	v_div_fmas_f32 v117, v117, v119, v129
	v_div_fixup_f32 v127, v117, v127, 1.0
	v_div_scale_f32 v117, s[0:1], v126, v126, 1.0
	v_rcp_f32_e32 v119, v117
	s_nop 0
	v_fma_f32 v128, -v117, v119, 1.0
	v_fmac_f32_e32 v119, v128, v119
	v_div_scale_f32 v128, vcc, 1.0, v126, 1.0
	v_mul_f32_e32 v129, v128, v119
	v_fma_f32 v130, -v117, v129, v128
	v_fmac_f32_e32 v129, v130, v119
	v_fma_f32 v117, -v117, v129, v128
	v_div_fmas_f32 v117, v117, v119, v129
	v_pk_mul_f32 v[128:129], v[4:5], v[66:67]
	v_div_fixup_f32 v126, v117, v126, 1.0
	v_pk_fma_f32 v[76:77], v[12:13], v[76:77], v[128:129]
	v_and_b32_e32 v117, 0xffff0000, v116
	v_lshlrev_b32_e32 v116, 16, v116
	v_pk_fma_f32 v[76:77], v[8:9], v[74:75], v[76:77]
	v_pk_mul_f32 v[68:69], v[68:69], v[126:127]
	v_pk_fma_f32 v[76:77], v[36:37], v[116:117], v[76:77]
	v_pk_mul_f32 v[126:127], v[68:69], v[68:69]
	v_mul_f32_e32 v119, 0xbfb8aa3b, v76
	v_exp_f32_e32 v128, v119
	v_mul_f32_e32 v119, 0xbfb8aa3b, v77
	v_exp_f32_e32 v129, v119
	s_nop 0
	v_pk_add_f32 v[128:129], v[128:129], 1.0 op_sel_hi:[1,0]
	s_nop 0
	v_div_scale_f32 v119, s[0:1], v129, v129, 1.0
	v_rcp_f32_e32 v130, v119
	s_nop 0
	v_fma_f32 v131, -v119, v130, 1.0
	v_fmac_f32_e32 v130, v131, v130
	v_div_scale_f32 v131, vcc, 1.0, v129, 1.0
	v_mul_f32_e32 v132, v131, v130
	v_fma_f32 v133, -v119, v132, v131
	v_fmac_f32_e32 v132, v133, v130
	v_fma_f32 v119, -v119, v132, v131
	v_div_fmas_f32 v119, v119, v130, v132
	v_div_fixup_f32 v129, v119, v129, 1.0
	v_div_scale_f32 v119, s[0:1], v128, v128, 1.0
	v_rcp_f32_e32 v130, v119
	s_nop 0
	v_fma_f32 v131, -v119, v130, 1.0
	v_fmac_f32_e32 v130, v131, v130
	v_div_scale_f32 v131, vcc, 1.0, v128, 1.0
	v_mul_f32_e32 v132, v131, v130
	v_fma_f32 v133, -v119, v132, v131
	v_fmac_f32_e32 v132, v133, v130
	v_fma_f32 v119, -v119, v132, v131
	v_div_fmas_f32 v119, v119, v130, v132
	v_div_fixup_f32 v128, v119, v128, 1.0
	v_pk_mul_f32 v[76:77], v[76:77], v[128:129]
	v_mov_b32_e32 v131, v122
	v_pk_mul_f32 v[128:129], v[76:77], v[76:77]
	s_nop 0
	v_mov_b32_e32 v130, v128
	v_mov_b32_e32 v122, v129
	v_pk_add_f32 v[122:123], v[130:131], v[122:123]
	v_mov_b32_e32 v128, v126
	v_mov_b32_e32 v129, v72
	v_pk_add_f32 v[122:123], v[128:129], v[122:123]
	v_mov_b32_e32 v72, v127
	v_pk_add_f32 v[72:73], v[72:73], v[122:123]
	v_mov_b32_e32 v123, v3
	v_mov_b32_e32 v122, v3
	s_nop 0
	v_mov_b32_dpp v123, v73 row_ror:8 row_mask:0xf bank_mask:0xf
	v_mov_b32_dpp v122, v72 row_ror:8 row_mask:0xf bank_mask:0xf
	v_pk_add_f32 v[72:73], v[72:73], v[122:123]
	v_mov_b32_e32 v123, v3
	v_mov_b32_e32 v122, v3
	s_nop 0
	v_mov_b32_dpp v123, v73 row_ror:4 row_mask:0xf bank_mask:0xf
	v_mov_b32_dpp v122, v72 row_ror:4 row_mask:0xf bank_mask:0xf
	v_pk_add_f32 v[72:73], v[72:73], v[122:123]
	v_mov_b32_e32 v123, v3
	v_mov_b32_e32 v122, v3
	s_nop 0
	v_mov_b32_dpp v123, v73 row_ror:2 row_mask:0xf bank_mask:0xf
	v_mov_b32_dpp v122, v72 row_ror:2 row_mask:0xf bank_mask:0xf
	v_pk_add_f32 v[72:73], v[72:73], v[122:123]
	v_mov_b32_e32 v123, v3
	v_mov_b32_e32 v122, v3
	s_nop 0
	v_mov_b32_dpp v123, v73 row_ror:1 row_mask:0xf bank_mask:0xf
	v_mov_b32_dpp v122, v72 row_ror:1 row_mask:0xf bank_mask:0xf
	v_pk_add_f32 v[72:73], v[72:73], v[122:123]
	ds_bpermute_b32 v123, v81, v73
	ds_bpermute_b32 v122, v81, v72
	s_waitcnt lgkmcnt(0)
; __device__ __forceinline__ float bf2f(bf16 v) { return __uint_as_float(((unsigned)v) << 16); }
; __device__ __forceinline__ float siluf_(float x) { return x * sigmoidf_(x); }
; __device__ __forceinline__ unsigned cvt2(float lo, float hi) { f32x2 v = {lo, hi}; return __builtin_bit_cast(unsigned, __builtin_convertvector(v, bf16x2_t)); }
; template <int STRIP> __device__ __forceinline__ void ph_gdn_prep_fast(const bf16* __restrict__ proj, const float* __restrict__ small, const float* __restrict__ conv_w, const float* __restrict__ a_log, const float* __restrict__ dt_bias, ...
;     ...
;                 for (int which = 0; which < 3; ++which) {
;                     float xf[7][4];
; #pragma unroll
;                     for (int r = 0; r < 7; ++r) { xf[r][0] = bf2f((bf16)(xr[which][r].x & 0xffff)); xf[r][1] = bf2f((bf16)(xr[which][r].x >> 16)); xf[r][2] = bf2f((bf16)(xr[which][r].y & 0xffff)); xf[r][3] = bf2f((bf16)(xr[which][r].y >> 16)); }
; #pragma unroll
;                     for (int j = 0; j < 4; ++j) { float y[4]; float ss = 0.f;
; #pragma unroll
;                         for (int e = 0; e < 4; ++e) { float v = cw[which][0][e] * xf[j][e]; v += cw[which][1][e] * xf[j + 1][e]; v += cw[which][2][e] * xf[j + 2][e]; v += cw[which][3][e] * xf[j + 3][e]; y[e] = siluf_(v); ss += y[e] * y[e]; }
;                         float r = 1.f;
;                         if (which < 2) { ss = row16_sum(ss); ss += __shfl_xor(ss, 16); r = rsqrtf(ss + NORM_EPS); if (which == 0) r *= 0.08838834764831845f; }
;                         u32x2 o; o.x = cvt2(y[0] * r, y[1] * r); o.y = cvt2(y[2] * r, y[3] * r);
;                         *(u32x2*)(L + which * (64 * GP_STR * 2) + ((4 * ts + j) * GP_STR + 4 * cg) * 2) = o; }
	v_pk_add_f32 v[72:73], v[72:73], v[122:123]
	s_nop 0
	v_pk_add_f32 v[72:73], v[72:73], s[82:83] op_sel_hi:[1,0]
	s_nop 0
	v_mul_f32_e32 v119, 0x4b800000, v73
	v_cmp_gt_f32_e64 s[0:1], s22, v73
	v_cmp_gt_f32_e32 vcc, s22, v72
	s_nop 0
	v_cndmask_b32_e64 v73, v73, v119, s[0:1]
	v_rsq_f32_e32 v73, v73
	s_nop 0
	v_mul_f32_e32 v119, 0x45800000, v73
	v_cndmask_b32_e64 v73, v73, v119, s[0:1]
	v_mul_f32_e32 v122, 0x3db504f3, v73
	v_pk_mul_f32 v[120:121], v[120:121], v[122:123] op_sel_hi:[1,0]
	v_pk_mul_f32 v[70:71], v[70:71], v[122:123] op_sel_hi:[1,0]
	v_cvt_pk_bf16_f32 v120, v120, v121
	v_cvt_pk_bf16_f32 v121, v70, v71
	v_mul_f32_e32 v70, 0x4b800000, v72
	v_cndmask_b32_e32 v70, v72, v70, vcc
	v_rsq_f32_e32 v70, v70
	s_nop 0
	v_mul_f32_e32 v71, 0x45800000, v70
	v_cndmask_b32_e32 v70, v70, v71, vcc
	v_mul_f32_e32 v70, 0x3db504f3, v70
	v_pk_mul_f32 v[72:73], v[76:77], v[70:71] op_sel_hi:[1,0]
	v_pk_mul_f32 v[68:69], v[68:69], v[70:71] op_sel_hi:[1,0]
	v_pk_mul_f32 v[70:71], v[6:7], v[64:65]
	v_cvt_pk_bf16_f32 v72, v72, v73
	v_pk_fma_f32 v[62:63], v[14:15], v[62:63], v[70:71]
	v_cvt_pk_bf16_f32 v73, v68, v69
	v_and_b32_e32 v69, 0xffff0000, v115
	v_lshlrev_b32_e32 v68, 16, v115
	v_pk_fma_f32 v[62:63], v[10:11], v[124:125], v[62:63]
	ds_write2_b64 v87, v[120:121], v[72:73] offset1:34
	v_pk_fma_f32 v[62:63], v[38:39], v[68:69], v[62:63]
	s_nop 0
	v_mul_f32_e32 v70, 0xbfb8aa3b, v62
	v_mul_f32_e32 v71, 0xbfb8aa3b, v63
	v_exp_f32_e32 v70, v70
	v_exp_f32_e32 v71, v71
	s_nop 0
	v_pk_add_f32 v[70:71], v[70:71], 1.0 op_sel_hi:[1,0]
	s_nop 0
	v_div_scale_f32 v72, s[0:1], v71, v71, 1.0
	v_rcp_f32_e32 v73, v72
	s_nop 0
	v_fma_f32 v76, -v72, v73, 1.0
	v_fmac_f32_e32 v73, v76, v73
	v_div_scale_f32 v76, vcc, 1.0, v71, 1.0
	v_mul_f32_e32 v77, v76, v73
	v_fma_f32 v115, -v72, v77, v76
	v_fmac_f32_e32 v77, v115, v73
	v_fma_f32 v72, -v72, v77, v76
	v_div_fmas_f32 v72, v72, v73, v77
	v_div_fixup_f32 v71, v72, v71, 1.0
	v_div_scale_f32 v72, s[0:1], v70, v70, 1.0
	v_rcp_f32_e32 v73, v72
	s_nop 0
	v_fma_f32 v76, -v72, v73, 1.0
	v_fmac_f32_e32 v73, v76, v73
	v_div_scale_f32 v76, vcc, 1.0, v70, 1.0
	v_mul_f32_e32 v77, v76, v73
	v_fma_f32 v115, -v72, v77, v76
	v_fmac_f32_e32 v77, v115, v73
	v_fma_f32 v72, -v72, v77, v76
	v_div_fmas_f32 v72, v72, v73, v77
	v_pk_mul_f32 v[76:77], v[4:5], v[74:75]
	v_div_fixup_f32 v70, v72, v70, 1.0
	v_pk_fma_f32 v[66:67], v[12:13], v[66:67], v[76:77]
	v_and_b32_e32 v73, 0xffff0000, v113
	v_lshlrev_b32_e32 v72, 16, v113
	v_pk_fma_f32 v[66:67], v[8:9], v[116:117], v[66:67]
	v_pk_mul_f32 v[116:117], v[4:5], v[116:117]
	v_pk_fma_f32 v[66:67], v[36:37], v[72:73], v[66:67]
	v_pk_fma_f32 v[74:75], v[12:13], v[74:75], v[116:117]
	v_mul_f32_e32 v76, 0xbfb8aa3b, v66
	v_mul_f32_e32 v77, 0xbfb8aa3b, v67
	v_exp_f32_e32 v76, v76
	v_exp_f32_e32 v77, v77
	v_pk_fma_f32 v[72:73], v[8:9], v[72:73], v[74:75]
	v_pk_mul_f32 v[62:63], v[62:63], v[70:71]
	v_pk_add_f32 v[76:77], v[76:77], 1.0 op_sel_hi:[1,0]
	s_nop 0
	v_div_scale_f32 v113, s[0:1], v77, v77, 1.0
	v_rcp_f32_e32 v115, v113
	v_pk_mul_f32 v[70:71], v[62:63], v[62:63]
	v_fma_f32 v119, -v113, v115, 1.0
	v_fmac_f32_e32 v115, v119, v115
	v_div_scale_f32 v119, vcc, 1.0, v77, 1.0
	v_mul_f32_e32 v120, v119, v115
	v_fma_f32 v121, -v113, v120, v119
	v_fmac_f32_e32 v120, v121, v115
	v_fma_f32 v113, -v113, v120, v119
	v_div_fmas_f32 v113, v113, v115, v120
	v_div_fixup_f32 v77, v113, v77, 1.0
	v_div_scale_f32 v113, s[0:1], v76, v76, 1.0
	v_rcp_f32_e32 v115, v113
	s_nop 0
	v_fma_f32 v119, -v113, v115, 1.0
	v_fmac_f32_e32 v115, v119, v115
	v_div_scale_f32 v119, vcc, 1.0, v76, 1.0
	v_mul_f32_e32 v120, v119, v115
	v_fma_f32 v121, -v113, v120, v119
	v_fmac_f32_e32 v120, v121, v115
	v_fma_f32 v113, -v113, v120, v119
	v_div_fmas_f32 v113, v113, v115, v120
	v_pk_mul_f32 v[120:121], v[6:7], v[124:125]
	v_and_b32_e32 v115, 0xffff0000, v114
	v_pk_fma_f32 v[64:65], v[14:15], v[64:65], v[120:121]
	v_lshlrev_b32_e32 v114, 16, v114
	v_pk_fma_f32 v[64:65], v[10:11], v[68:69], v[64:65]
	v_div_fixup_f32 v76, v113, v76, 1.0
	v_pk_fma_f32 v[64:65], v[38:39], v[114:115], v[64:65]
	v_pk_mul_f32 v[66:67], v[66:67], v[76:77]
	v_mul_f32_e32 v68, 0xbfb8aa3b, v64
	v_mul_f32_e32 v69, 0xbfb8aa3b, v65
	v_exp_f32_e32 v68, v68
	v_exp_f32_e32 v69, v69
	v_pk_mul_f32 v[76:77], v[66:67], v[66:67]
	v_pk_add_f32 v[68:69], v[68:69], 1.0 op_sel_hi:[1,0]
	s_nop 0
	v_div_scale_f32 v113, s[0:1], v69, v69, 1.0
	v_rcp_f32_e32 v114, v113
	s_nop 0
	v_fma_f32 v115, -v113, v114, 1.0
	v_fmac_f32_e32 v114, v115, v114
	v_div_scale_f32 v115, vcc, 1.0, v69, 1.0
	v_mul_f32_e32 v119, v115, v114
	v_fma_f32 v120, -v113, v119, v115
	v_fmac_f32_e32 v119, v120, v114
	v_fma_f32 v113, -v113, v119, v115
	v_div_fmas_f32 v113, v113, v114, v119
	v_div_fixup_f32 v69, v113, v69, 1.0
	v_div_scale_f32 v113, s[0:1], v68, v68, 1.0
	v_rcp_f32_e32 v114, v113
	s_nop 0
	v_fma_f32 v115, -v113, v114, 1.0
	v_fmac_f32_e32 v114, v115, v114
	v_div_scale_f32 v115, vcc, 1.0, v68, 1.0
	v_mul_f32_e32 v119, v115, v114
	v_fma_f32 v120, -v113, v119, v115
	v_fmac_f32_e32 v119, v120, v114
	v_fma_f32 v113, -v113, v119, v115
	v_div_fmas_f32 v113, v113, v114, v119
	v_and_b32_e32 v115, 0xffff0000, v2
	v_lshlrev_b32_e32 v114, 16, v2
	v_pk_fma_f32 v[72:73], v[36:37], v[114:115], v[72:73]
	v_div_fixup_f32 v68, v113, v68, 1.0
	v_mul_f32_e32 v2, 0xbfb8aa3b, v72
	v_exp_f32_e32 v74, v2
	v_mul_f32_e32 v2, 0xbfb8aa3b, v73
	v_exp_f32_e32 v75, v2
	v_pk_mul_f32 v[64:65], v[64:65], v[68:69]
	v_pk_add_f32 v[74:75], v[74:75], 1.0 op_sel_hi:[1,0]
	s_nop 0
	v_div_scale_f32 v2, s[0:1], v75, v75, 1.0
	v_rcp_f32_e32 v113, v2
	v_pk_mul_f32 v[68:69], v[64:65], v[64:65]
	v_fma_f32 v114, -v2, v113, 1.0
	v_fmac_f32_e32 v113, v114, v113
; __device__ __forceinline__ float bf2f(bf16 v) { return __uint_as_float(((unsigned)v) << 16); }
; __device__ __forceinline__ float siluf_(float x) { return x * sigmoidf_(x); }
; __device__ __forceinline__ unsigned cvt2(float lo, float hi) { f32x2 v = {lo, hi}; return __builtin_bit_cast(unsigned, __builtin_convertvector(v, bf16x2_t)); }
; template <int STRIP> __device__ __forceinline__ void ph_gdn_prep_fast(const bf16* __restrict__ proj, const float* __restrict__ small, const float* __restrict__ conv_w, const float* __restrict__ a_log, const float* __restrict__ dt_bias, ...
;     ...
;                 for (int which = 0; which < 3; ++which) {
;                     float xf[7][4];
; #pragma unroll
;                     for (int r = 0; r < 7; ++r) { xf[r][0] = bf2f((bf16)(xr[which][r].x & 0xffff)); xf[r][1] = bf2f((bf16)(xr[which][r].x >> 16)); xf[r][2] = bf2f((bf16)(xr[which][r].y & 0xffff)); xf[r][3] = bf2f((bf16)(xr[which][r].y >> 16)); }
; #pragma unroll
;                     for (int j = 0; j < 4; ++j) { float y[4]; float ss = 0.f;
; #pragma unroll
;                         for (int e = 0; e < 4; ++e) { float v = cw[which][0][e] * xf[j][e]; v += cw[which][1][e] * xf[j + 1][e]; v += cw[which][2][e] * xf[j + 2][e]; v += cw[which][3][e] * xf[j + 3][e]; y[e] = siluf_(v); ss += y[e] * y[e]; }
;                         float r = 1.f;
;                         if (which < 2) { ss = row16_sum(ss); ss += __shfl_xor(ss, 16); r = rsqrtf(ss + NORM_EPS); if (which == 0) r *= 0.08838834764831845f; }
;                         u32x2 o; o.x = cvt2(y[0] * r, y[1] * r); o.y = cvt2(y[2] * r, y[3] * r);
;                         *(u32x2*)(L + which * (64 * GP_STR * 2) + ((4 * ts + j) * GP_STR + 4 * cg) * 2) = o; }
	v_div_scale_f32 v114, vcc, 1.0, v75, 1.0
	v_mul_f32_e32 v115, v114, v113
	v_fma_f32 v116, -v2, v115, v114
	v_fmac_f32_e32 v115, v116, v113
	v_fma_f32 v2, -v2, v115, v114
	v_div_fmas_f32 v2, v2, v113, v115
	v_div_fixup_f32 v75, v2, v75, 1.0
	v_div_scale_f32 v2, s[0:1], v74, v74, 1.0
	v_rcp_f32_e32 v113, v2
	s_nop 0
	v_fma_f32 v114, -v2, v113, 1.0
	v_fmac_f32_e32 v113, v114, v113
	v_div_scale_f32 v114, vcc, 1.0, v74, 1.0
	v_mul_f32_e32 v115, v114, v113
	v_fma_f32 v116, -v2, v115, v114
	v_fmac_f32_e32 v115, v116, v113
	v_fma_f32 v2, -v2, v115, v114
	v_div_fmas_f32 v2, v2, v113, v115
	v_div_fixup_f32 v74, v2, v74, 1.0
	v_pk_mul_f32 v[72:73], v[72:73], v[74:75]
	v_mov_b32_e32 v115, v76
	v_pk_mul_f32 v[74:75], v[72:73], v[72:73]
	s_nop 0
	v_mov_b32_e32 v114, v74
	v_mov_b32_e32 v76, v75
	v_pk_add_f32 v[74:75], v[114:115], v[76:77]
	v_mov_b32_e32 v76, v68
	v_mov_b32_e32 v77, v70
	v_pk_add_f32 v[74:75], v[76:77], v[74:75]
	v_mov_b32_e32 v70, v69
	v_pk_add_f32 v[68:69], v[70:71], v[74:75]
	v_mov_b32_e32 v71, v3
	v_mov_b32_e32 v70, v3
	v_and_b32_e32 v77, 0xffff0000, v107
	v_mov_b32_dpp v71, v69 row_ror:8 row_mask:0xf bank_mask:0xf
	v_mov_b32_dpp v70, v68 row_ror:8 row_mask:0xf bank_mask:0xf
	v_pk_add_f32 v[68:69], v[68:69], v[70:71]
	v_mov_b32_e32 v71, v3
	v_mov_b32_e32 v70, v3
	s_nop 0
	v_mov_b32_dpp v71, v69 row_ror:4 row_mask:0xf bank_mask:0xf
	v_mov_b32_dpp v70, v68 row_ror:4 row_mask:0xf bank_mask:0xf
	v_pk_add_f32 v[68:69], v[68:69], v[70:71]
	v_mov_b32_e32 v71, v3
	v_mov_b32_e32 v70, v3
	s_nop 0
	v_mov_b32_dpp v71, v69 row_ror:2 row_mask:0xf bank_mask:0xf
	v_mov_b32_dpp v70, v68 row_ror:2 row_mask:0xf bank_mask:0xf
	v_pk_add_f32 v[68:69], v[68:69], v[70:71]
	v_mov_b32_e32 v71, v3
	v_mov_b32_e32 v70, v3
	s_nop 0
	v_mov_b32_dpp v71, v69 row_ror:1 row_mask:0xf bank_mask:0xf
	v_mov_b32_dpp v70, v68 row_ror:1 row_mask:0xf bank_mask:0xf
	v_pk_add_f32 v[68:69], v[68:69], v[70:71]
	ds_bpermute_b32 v71, v81, v69
	ds_bpermute_b32 v70, v81, v68
	s_waitcnt lgkmcnt(0)
	v_pk_add_f32 v[68:69], v[68:69], v[70:71]
	s_nop 0
	v_pk_add_f32 v[68:69], v[68:69], s[82:83] op_sel_hi:[1,0]
	s_nop 0
	v_mul_f32_e32 v2, 0x4b800000, v69
	v_cmp_gt_f32_e64 s[0:1], s22, v69
	v_cmp_gt_f32_e32 vcc, s22, v68
	s_nop 0
	v_cndmask_b32_e64 v2, v69, v2, s[0:1]
	v_rsq_f32_e32 v2, v2
	s_nop 0
	v_mul_f32_e32 v69, 0x45800000, v2
	v_cndmask_b32_e64 v2, v2, v69, s[0:1]
	v_mul_f32_e32 v2, 0x3db504f3, v2
	v_pk_mul_f32 v[66:67], v[66:67], v[2:3] op_sel_hi:[1,0]
	v_pk_mul_f32 v[62:63], v[62:63], v[2:3] op_sel_hi:[1,0]
	v_mul_f32_e32 v2, 0x4b800000, v68
	v_cndmask_b32_e32 v2, v68, v2, vcc
	v_rsq_f32_e32 v2, v2
	v_cvt_pk_bf16_f32 v66, v66, v67
	v_cvt_pk_bf16_f32 v67, v62, v63
	ds_write_b64 v87, v[66:67] offset:544
	v_mul_f32_e32 v62, 0x45800000, v2
	v_cndmask_b32_e32 v2, v2, v62, vcc
	v_mul_f32_e32 v2, 0x3db504f3, v2
	v_pk_mul_f32 v[62:63], v[72:73], v[2:3] op_sel_hi:[1,0]
	v_pk_mul_f32 v[64:65], v[64:65], v[2:3] op_sel_hi:[1,0]
	v_cvt_pk_bf16_f32 v62, v62, v63
	v_cvt_pk_bf16_f32 v63, v64, v65
	v_and_b32_e32 v65, 0xffff0000, v111
	v_lshlrev_b32_e32 v64, 16, v111
	v_add_u32_e32 v2, v118, v83
	v_and_b32_e32 v67, 0xffff0000, v110
	v_lshlrev_b32_e32 v66, 16, v110
	v_pk_mul_f32 v[70:71], v[30:31], v[64:65]
	ds_write_b64 v2, v[62:63]
	v_and_b32_e32 v63, 0xffff0000, v112
	v_lshlrev_b32_e32 v62, 16, v112
	v_pk_fma_f32 v[66:67], v[18:19], v[66:67], v[70:71]
	v_and_b32_e32 v69, 0xffff0000, v109
	v_lshlrev_b32_e32 v68, 16, v109
	v_pk_fma_f32 v[66:67], v[22:23], v[62:63], v[66:67]
	v_and_b32_e32 v111, 0xffff0000, v106
	v_pk_fma_f32 v[66:67], v[26:27], v[68:69], v[66:67]
	v_lshlrev_b32_e32 v110, 16, v106
	v_mul_f32_e32 v70, 0xbfb8aa3b, v66
	v_mul_f32_e32 v71, 0xbfb8aa3b, v67
	v_exp_f32_e32 v70, v70
	v_exp_f32_e32 v71, v71
	s_nop 0
	v_pk_add_f32 v[70:71], v[70:71], 1.0 op_sel_hi:[1,0]
	s_nop 0
	v_div_scale_f32 v72, s[0:1], v71, v71, 1.0
	v_rcp_f32_e32 v73, v72
	s_nop 0
	v_fma_f32 v74, -v72, v73, 1.0
	v_fmac_f32_e32 v73, v74, v73
	v_div_scale_f32 v74, vcc, 1.0, v71, 1.0
	v_mul_f32_e32 v75, v74, v73
	v_fma_f32 v76, -v72, v75, v74
	v_fmac_f32_e32 v75, v76, v73
	v_fma_f32 v72, -v72, v75, v74
	v_div_fmas_f32 v72, v72, v73, v75
	v_div_fixup_f32 v71, v72, v71, 1.0
	v_div_scale_f32 v72, s[0:1], v70, v70, 1.0
	v_rcp_f32_e32 v73, v72
	s_nop 0
	v_fma_f32 v74, -v72, v73, 1.0
	v_fmac_f32_e32 v73, v74, v73
	v_div_scale_f32 v74, vcc, 1.0, v70, 1.0
	v_mul_f32_e32 v75, v74, v73
	v_fma_f32 v76, -v72, v75, v74
	v_fmac_f32_e32 v75, v76, v73
	v_fma_f32 v72, -v72, v75, v74
	v_div_fmas_f32 v72, v72, v73, v75
	v_lshlrev_b32_e32 v76, 16, v107
	v_div_fixup_f32 v70, v72, v70, 1.0
	v_pk_mul_f32 v[106:107], v[28:29], v[76:77]
	v_pk_mul_f32 v[70:71], v[66:67], v[70:71]
	v_and_b32_e32 v67, 0xffff0000, v108
	v_lshlrev_b32_e32 v66, 16, v108
	v_pk_fma_f32 v[106:107], v[16:17], v[110:111], v[106:107]
	v_and_b32_e32 v75, 0xffff0000, v105
	v_lshlrev_b32_e32 v74, 16, v105
	v_pk_fma_f32 v[106:107], v[20:21], v[66:67], v[106:107]
	v_pk_mul_f32 v[72:73], v[70:71], v[70:71]
	v_pk_fma_f32 v[106:107], v[24:25], v[74:75], v[106:107]
	s_nop 0
	v_mul_f32_e32 v105, 0xbfb8aa3b, v106
	v_exp_f32_e32 v108, v105
	v_mul_f32_e32 v105, 0xbfb8aa3b, v107
	v_exp_f32_e32 v109, v105
	s_nop 0
	v_pk_add_f32 v[108:109], v[108:109], 1.0 op_sel_hi:[1,0]
	s_nop 0
	v_div_scale_f32 v105, s[0:1], v109, v109, 1.0
	v_rcp_f32_e32 v110, v105
	s_nop 0
	v_fma_f32 v111, -v105, v110, 1.0
	v_fmac_f32_e32 v110, v111, v110
	v_div_scale_f32 v111, vcc, 1.0, v109, 1.0
	v_mul_f32_e32 v112, v111, v110
	v_fma_f32 v113, -v105, v112, v111
	v_fmac_f32_e32 v112, v113, v110
	v_fma_f32 v105, -v105, v112, v111
	v_div_fmas_f32 v105, v105, v110, v112
	v_div_fixup_f32 v109, v105, v109, 1.0
; __device__ __forceinline__ float bf2f(bf16 v) { return __uint_as_float(((unsigned)v) << 16); }
; __device__ __forceinline__ float siluf_(float x) { return x * sigmoidf_(x); }
; __device__ __forceinline__ unsigned cvt2(float lo, float hi) { f32x2 v = {lo, hi}; return __builtin_bit_cast(unsigned, __builtin_convertvector(v, bf16x2_t)); }
; template <int STRIP> __device__ __forceinline__ void ph_gdn_prep_fast(const bf16* __restrict__ proj, const float* __restrict__ small, const float* __restrict__ conv_w, const float* __restrict__ a_log, const float* __restrict__ dt_bias, ...
;     ...
;                 for (int which = 0; which < 3; ++which) {
;                     float xf[7][4];
; #pragma unroll
;                     for (int r = 0; r < 7; ++r) { xf[r][0] = bf2f((bf16)(xr[which][r].x & 0xffff)); xf[r][1] = bf2f((bf16)(xr[which][r].x >> 16)); xf[r][2] = bf2f((bf16)(xr[which][r].y & 0xffff)); xf[r][3] = bf2f((bf16)(xr[which][r].y >> 16)); }
; #pragma unroll
;                     for (int j = 0; j < 4; ++j) { float y[4]; float ss = 0.f;
; #pragma unroll
;                         for (int e = 0; e < 4; ++e) { float v = cw[which][0][e] * xf[j][e]; v += cw[which][1][e] * xf[j + 1][e]; v += cw[which][2][e] * xf[j + 2][e]; v += cw[which][3][e] * xf[j + 3][e]; y[e] = siluf_(v); ss += y[e] * y[e]; }
;                         float r = 1.f;
;                         if (which < 2) { ss = row16_sum(ss); ss += __shfl_xor(ss, 16); r = rsqrtf(ss + NORM_EPS); if (which == 0) r *= 0.08838834764831845f; }
;                         u32x2 o; o.x = cvt2(y[0] * r, y[1] * r); o.y = cvt2(y[2] * r, y[3] * r);
;                         *(u32x2*)(L + which * (64 * GP_STR * 2) + ((4 * ts + j) * GP_STR + 4 * cg) * 2) = o; }
	v_div_scale_f32 v105, s[0:1], v108, v108, 1.0
	v_rcp_f32_e32 v110, v105
	s_nop 0
	v_fma_f32 v111, -v105, v110, 1.0
	v_fmac_f32_e32 v110, v111, v110
	v_div_scale_f32 v111, vcc, 1.0, v108, 1.0
	v_mul_f32_e32 v112, v111, v110
	v_fma_f32 v113, -v105, v112, v111
	v_fmac_f32_e32 v112, v113, v110
	v_fma_f32 v105, -v105, v112, v111
	v_div_fmas_f32 v105, v105, v110, v112
	v_pk_mul_f32 v[110:111], v[30:31], v[62:63]
	v_div_fixup_f32 v108, v105, v108, 1.0
	v_pk_fma_f32 v[64:65], v[18:19], v[64:65], v[110:111]
	v_and_b32_e32 v105, 0xffff0000, v104
	v_lshlrev_b32_e32 v104, 16, v104
	v_pk_fma_f32 v[64:65], v[22:23], v[68:69], v[64:65]
	v_pk_mul_f32 v[106:107], v[106:107], v[108:109]
	v_pk_fma_f32 v[64:65], v[26:27], v[104:105], v[64:65]
	v_pk_mul_f32 v[108:109], v[106:107], v[106:107]
	v_mul_f32_e32 v110, 0xbfb8aa3b, v64
	v_mul_f32_e32 v111, 0xbfb8aa3b, v65
	v_exp_f32_e32 v110, v110
	v_exp_f32_e32 v111, v111
	s_nop 0
	v_pk_add_f32 v[110:111], v[110:111], 1.0 op_sel_hi:[1,0]
	s_nop 0
	v_div_scale_f32 v112, s[0:1], v111, v111, 1.0
	v_rcp_f32_e32 v113, v112
	s_nop 0
	v_fma_f32 v114, -v112, v113, 1.0
	v_fmac_f32_e32 v113, v114, v113
	v_div_scale_f32 v114, vcc, 1.0, v111, 1.0
	v_mul_f32_e32 v115, v114, v113
	v_fma_f32 v116, -v112, v115, v114
	v_fmac_f32_e32 v115, v116, v113
	v_fma_f32 v112, -v112, v115, v114
	v_div_fmas_f32 v112, v112, v113, v115
	v_div_fixup_f32 v111, v112, v111, 1.0
	v_div_scale_f32 v112, s[0:1], v110, v110, 1.0
	v_rcp_f32_e32 v113, v112
	s_nop 0
	v_fma_f32 v114, -v112, v113, 1.0
	v_fmac_f32_e32 v113, v114, v113
	v_div_scale_f32 v114, vcc, 1.0, v110, 1.0
	v_mul_f32_e32 v115, v114, v113
	v_fma_f32 v116, -v112, v115, v114
	v_fmac_f32_e32 v115, v116, v113
	v_fma_f32 v112, -v112, v115, v114
	v_div_fmas_f32 v112, v112, v113, v115
	v_pk_mul_f32 v[114:115], v[28:29], v[66:67]
	v_div_fixup_f32 v110, v112, v110, 1.0
	v_pk_fma_f32 v[76:77], v[16:17], v[76:77], v[114:115]
	v_and_b32_e32 v113, 0xffff0000, v103
	v_lshlrev_b32_e32 v112, 16, v103
	v_pk_fma_f32 v[76:77], v[20:21], v[74:75], v[76:77]
	v_pk_mul_f32 v[64:65], v[64:65], v[110:111]
	v_pk_fma_f32 v[76:77], v[24:25], v[112:113], v[76:77]
	v_pk_mul_f32 v[110:111], v[64:65], v[64:65]
	v_mul_f32_e32 v103, 0xbfb8aa3b, v76
	v_exp_f32_e32 v114, v103
	v_mul_f32_e32 v103, 0xbfb8aa3b, v77
	v_exp_f32_e32 v115, v103
	s_nop 0
	v_pk_add_f32 v[114:115], v[114:115], 1.0 op_sel_hi:[1,0]
	s_nop 0
	v_div_scale_f32 v103, s[0:1], v115, v115, 1.0
	v_rcp_f32_e32 v116, v103
	s_nop 0
	v_fma_f32 v117, -v103, v116, 1.0
	v_fmac_f32_e32 v116, v117, v116
	v_div_scale_f32 v117, vcc, 1.0, v115, 1.0
	v_mul_f32_e32 v118, v117, v116
	v_fma_f32 v119, -v103, v118, v117
	v_fmac_f32_e32 v118, v119, v116
	v_fma_f32 v103, -v103, v118, v117
	v_div_fmas_f32 v103, v103, v116, v118
	v_div_fixup_f32 v115, v103, v115, 1.0
	v_div_scale_f32 v103, s[0:1], v114, v114, 1.0
	v_rcp_f32_e32 v116, v103
	s_nop 0
	v_fma_f32 v117, -v103, v116, 1.0
	v_fmac_f32_e32 v116, v117, v116
	v_div_scale_f32 v117, vcc, 1.0, v114, 1.0
	v_mul_f32_e32 v118, v117, v116
	v_fma_f32 v119, -v103, v118, v117
	v_fmac_f32_e32 v118, v119, v116
	v_fma_f32 v103, -v103, v118, v117
	v_div_fmas_f32 v103, v103, v116, v118
	v_div_fixup_f32 v114, v103, v114, 1.0
	v_pk_mul_f32 v[76:77], v[76:77], v[114:115]
	v_mov_b32_e32 v117, v108
	v_pk_mul_f32 v[114:115], v[76:77], v[76:77]
	s_nop 0
	v_mov_b32_e32 v116, v114
	v_mov_b32_e32 v108, v115
	v_pk_add_f32 v[108:109], v[116:117], v[108:109]
	v_mov_b32_e32 v114, v110
	v_mov_b32_e32 v115, v72
	v_pk_add_f32 v[108:109], v[114:115], v[108:109]
	v_mov_b32_e32 v72, v111
	v_pk_add_f32 v[72:73], v[72:73], v[108:109]
	v_mov_b32_e32 v109, v3
	v_mov_b32_e32 v108, v3
	s_nop 0
	v_mov_b32_dpp v109, v73 row_ror:8 row_mask:0xf bank_mask:0xf
	v_mov_b32_dpp v108, v72 row_ror:8 row_mask:0xf bank_mask:0xf
	v_pk_add_f32 v[72:73], v[72:73], v[108:109]
	v_mov_b32_e32 v109, v3
	v_mov_b32_e32 v108, v3
	s_nop 0
	v_mov_b32_dpp v109, v73 row_ror:4 row_mask:0xf bank_mask:0xf
	v_mov_b32_dpp v108, v72 row_ror:4 row_mask:0xf bank_mask:0xf
	v_pk_add_f32 v[72:73], v[72:73], v[108:109]
	v_mov_b32_e32 v109, v3
	v_mov_b32_e32 v108, v3
	s_nop 0
	v_mov_b32_dpp v109, v73 row_ror:2 row_mask:0xf bank_mask:0xf
	v_mov_b32_dpp v108, v72 row_ror:2 row_mask:0xf bank_mask:0xf
	v_pk_add_f32 v[72:73], v[72:73], v[108:109]
	v_mov_b32_e32 v109, v3
	v_mov_b32_e32 v108, v3
	s_nop 0
	v_mov_b32_dpp v109, v73 row_ror:1 row_mask:0xf bank_mask:0xf
	v_mov_b32_dpp v108, v72 row_ror:1 row_mask:0xf bank_mask:0xf
	v_pk_add_f32 v[72:73], v[72:73], v[108:109]
	ds_bpermute_b32 v109, v81, v73
	ds_bpermute_b32 v108, v81, v72
	s_waitcnt lgkmcnt(0)
; __device__ __forceinline__ float bf2f(bf16 v) { return __uint_as_float(((unsigned)v) << 16); }
; __device__ __forceinline__ float siluf_(float x) { return x * sigmoidf_(x); }
; __device__ __forceinline__ unsigned cvt2(float lo, float hi) { f32x2 v = {lo, hi}; return __builtin_bit_cast(unsigned, __builtin_convertvector(v, bf16x2_t)); }
; template <int STRIP> __device__ __forceinline__ void ph_gdn_prep_fast(const bf16* __restrict__ proj, const float* __restrict__ small, const float* __restrict__ conv_w, const float* __restrict__ a_log, const float* __restrict__ dt_bias, ...
;     ...
;                 for (int which = 0; which < 3; ++which) {
;                     float xf[7][4];
; #pragma unroll
;                     for (int r = 0; r < 7; ++r) { xf[r][0] = bf2f((bf16)(xr[which][r].x & 0xffff)); xf[r][1] = bf2f((bf16)(xr[which][r].x >> 16)); xf[r][2] = bf2f((bf16)(xr[which][r].y & 0xffff)); xf[r][3] = bf2f((bf16)(xr[which][r].y >> 16)); }
; #pragma unroll
;                     for (int j = 0; j < 4; ++j) { float y[4]; float ss = 0.f;
; #pragma unroll
;                         for (int e = 0; e < 4; ++e) { float v = cw[which][0][e] * xf[j][e]; v += cw[which][1][e] * xf[j + 1][e]; v += cw[which][2][e] * xf[j + 2][e]; v += cw[which][3][e] * xf[j + 3][e]; y[e] = siluf_(v); ss += y[e] * y[e]; }
;                         float r = 1.f;
;                         if (which < 2) { ss = row16_sum(ss); ss += __shfl_xor(ss, 16); r = rsqrtf(ss + NORM_EPS); if (which == 0) r *= 0.08838834764831845f; }
;                         u32x2 o; o.x = cvt2(y[0] * r, y[1] * r); o.y = cvt2(y[2] * r, y[3] * r);
;                         *(u32x2*)(L + which * (64 * GP_STR * 2) + ((4 * ts + j) * GP_STR + 4 * cg) * 2) = o; }
	v_pk_add_f32 v[72:73], v[72:73], v[108:109]
	s_nop 0
	v_pk_add_f32 v[72:73], v[72:73], s[82:83] op_sel_hi:[1,0]
	s_nop 0
	v_mul_f32_e32 v103, 0x4b800000, v73
	v_cmp_gt_f32_e64 s[0:1], s22, v73
	v_cmp_gt_f32_e32 vcc, s22, v72
	s_nop 0
	v_cndmask_b32_e64 v73, v73, v103, s[0:1]
	v_rsq_f32_e32 v73, v73
	s_nop 0
	v_mul_f32_e32 v103, 0x45800000, v73
	v_cndmask_b32_e64 v108, v73, v103, s[0:1]
	v_pk_mul_f32 v[106:107], v[106:107], v[108:109] op_sel_hi:[1,0]
	v_pk_mul_f32 v[70:71], v[70:71], v[108:109] op_sel_hi:[1,0]
	v_cvt_pk_bf16_f32 v106, v106, v107
	v_cvt_pk_bf16_f32 v107, v70, v71
	v_mul_f32_e32 v70, 0x4b800000, v72
	v_cndmask_b32_e32 v70, v72, v70, vcc
	v_rsq_f32_e32 v70, v70
	s_nop 0
	v_mul_f32_e32 v71, 0x45800000, v70
	v_cndmask_b32_e32 v70, v70, v71, vcc
	v_pk_mul_f32 v[72:73], v[76:77], v[70:71] op_sel_hi:[1,0]
	v_pk_mul_f32 v[64:65], v[64:65], v[70:71] op_sel_hi:[1,0]
	v_pk_mul_f32 v[70:71], v[30:31], v[68:69]
	v_cvt_pk_bf16_f32 v72, v72, v73
	v_cvt_pk_bf16_f32 v73, v64, v65
	v_add_u32_e32 v64, 0x4000, v87
	v_pk_fma_f32 v[62:63], v[18:19], v[62:63], v[70:71]
	ds_write2_b64 v64, v[106:107], v[72:73] offset0:128 offset1:162
	v_and_b32_e32 v65, 0xffff0000, v102
	v_lshlrev_b32_e32 v64, 16, v102
	v_pk_fma_f32 v[62:63], v[22:23], v[104:105], v[62:63]
	s_nop 0
	v_pk_fma_f32 v[62:63], v[26:27], v[64:65], v[62:63]
	s_nop 0
	v_mul_f32_e32 v70, 0xbfb8aa3b, v62
	v_mul_f32_e32 v71, 0xbfb8aa3b, v63
	v_exp_f32_e32 v70, v70
	v_exp_f32_e32 v71, v71
	s_nop 0
	v_pk_add_f32 v[70:71], v[70:71], 1.0 op_sel_hi:[1,0]
	s_nop 0
	v_div_scale_f32 v72, s[0:1], v71, v71, 1.0
	v_rcp_f32_e32 v73, v72
	s_nop 0
	v_fma_f32 v76, -v72, v73, 1.0
	v_fmac_f32_e32 v73, v76, v73
	v_div_scale_f32 v76, vcc, 1.0, v71, 1.0
	v_mul_f32_e32 v77, v76, v73
	v_fma_f32 v102, -v72, v77, v76
	v_fmac_f32_e32 v77, v102, v73
	v_fma_f32 v72, -v72, v77, v76
	v_div_fmas_f32 v72, v72, v73, v77
	v_div_fixup_f32 v71, v72, v71, 1.0
	v_div_scale_f32 v72, s[0:1], v70, v70, 1.0
	v_rcp_f32_e32 v73, v72
	s_nop 0
	v_fma_f32 v76, -v72, v73, 1.0
	v_fmac_f32_e32 v73, v76, v73
	v_div_scale_f32 v76, vcc, 1.0, v70, 1.0
	v_mul_f32_e32 v77, v76, v73
	v_fma_f32 v102, -v72, v77, v76
	v_fmac_f32_e32 v77, v102, v73
	v_fma_f32 v72, -v72, v77, v76
	v_div_fmas_f32 v72, v72, v73, v77
	v_pk_mul_f32 v[76:77], v[28:29], v[74:75]
	v_div_fixup_f32 v70, v72, v70, 1.0
	v_pk_fma_f32 v[66:67], v[16:17], v[66:67], v[76:77]
	v_and_b32_e32 v73, 0xffff0000, v101
	v_lshlrev_b32_e32 v72, 16, v101
	v_pk_fma_f32 v[66:67], v[20:21], v[112:113], v[66:67]
	v_pk_mul_f32 v[62:63], v[62:63], v[70:71]
	v_pk_fma_f32 v[66:67], v[24:25], v[72:73], v[66:67]
	v_pk_mul_f32 v[70:71], v[62:63], v[62:63]
	v_mul_f32_e32 v76, 0xbfb8aa3b, v66
	v_mul_f32_e32 v77, 0xbfb8aa3b, v67
	v_exp_f32_e32 v76, v76
	v_exp_f32_e32 v77, v77
	s_nop 0
	v_pk_add_f32 v[76:77], v[76:77], 1.0 op_sel_hi:[1,0]
	s_nop 0
	v_div_scale_f32 v101, s[0:1], v77, v77, 1.0
	v_rcp_f32_e32 v102, v101
	s_nop 0
	v_fma_f32 v103, -v101, v102, 1.0
	v_fmac_f32_e32 v102, v103, v102
	v_div_scale_f32 v103, vcc, 1.0, v77, 1.0
	v_mul_f32_e32 v106, v103, v102
	v_fma_f32 v107, -v101, v106, v103
	v_fmac_f32_e32 v106, v107, v102
	v_fma_f32 v101, -v101, v106, v103
	v_div_fmas_f32 v101, v101, v102, v106
	v_div_fixup_f32 v77, v101, v77, 1.0
	v_div_scale_f32 v101, s[0:1], v76, v76, 1.0
	v_rcp_f32_e32 v102, v101
	s_nop 0
	v_fma_f32 v103, -v101, v102, 1.0
	v_fmac_f32_e32 v102, v103, v102
	v_div_scale_f32 v103, vcc, 1.0, v76, 1.0
	v_mul_f32_e32 v106, v103, v102
	v_fma_f32 v107, -v101, v106, v103
	v_fmac_f32_e32 v106, v107, v102
	v_fma_f32 v101, -v101, v106, v103
	v_div_fmas_f32 v101, v101, v102, v106
	v_pk_mul_f32 v[102:103], v[30:31], v[104:105]
	v_div_fixup_f32 v76, v101, v76, 1.0
	v_pk_fma_f32 v[68:69], v[18:19], v[68:69], v[102:103]
	v_and_b32_e32 v101, 0xffff0000, v100
	v_lshlrev_b32_e32 v100, 16, v100
	v_pk_fma_f32 v[64:65], v[22:23], v[64:65], v[68:69]
	v_pk_mul_f32 v[66:67], v[66:67], v[76:77]
	v_pk_fma_f32 v[64:65], v[26:27], v[100:101], v[64:65]
	v_pk_mul_f32 v[76:77], v[66:67], v[66:67]
	v_mul_f32_e32 v68, 0xbfb8aa3b, v64
	v_mul_f32_e32 v69, 0xbfb8aa3b, v65
	v_exp_f32_e32 v68, v68
	v_exp_f32_e32 v69, v69
	s_nop 0
	v_pk_add_f32 v[68:69], v[68:69], 1.0 op_sel_hi:[1,0]
	s_nop 0
	v_div_scale_f32 v100, s[0:1], v69, v69, 1.0
	v_rcp_f32_e32 v101, v100
	s_nop 0
	v_fma_f32 v102, -v100, v101, 1.0
	v_fmac_f32_e32 v101, v102, v101
	v_div_scale_f32 v102, vcc, 1.0, v69, 1.0
	v_mul_f32_e32 v103, v102, v101
	v_fma_f32 v104, -v100, v103, v102
	v_fmac_f32_e32 v103, v104, v101
	v_fma_f32 v100, -v100, v103, v102
	v_div_fmas_f32 v100, v100, v101, v103
	v_div_fixup_f32 v69, v100, v69, 1.0
	v_div_scale_f32 v100, s[0:1], v68, v68, 1.0
	v_rcp_f32_e32 v101, v100
	s_nop 0
	v_fma_f32 v102, -v100, v101, 1.0
	v_fmac_f32_e32 v101, v102, v101
	v_div_scale_f32 v102, vcc, 1.0, v68, 1.0
	v_mul_f32_e32 v103, v102, v101
	v_fma_f32 v104, -v100, v103, v102
	v_fmac_f32_e32 v103, v104, v101
	v_fma_f32 v100, -v100, v103, v102
	v_div_fmas_f32 v100, v100, v101, v103
	v_pk_mul_f32 v[102:103], v[28:29], v[112:113]
	v_div_fixup_f32 v68, v100, v68, 1.0
	v_pk_fma_f32 v[74:75], v[16:17], v[74:75], v[102:103]
	v_and_b32_e32 v101, 0xffff0000, v99
	v_lshlrev_b32_e32 v100, 16, v99
	v_pk_fma_f32 v[72:73], v[20:21], v[72:73], v[74:75]
	v_pk_mul_f32 v[64:65], v[64:65], v[68:69]
	v_pk_fma_f32 v[72:73], v[24:25], v[100:101], v[72:73]
	v_pk_mul_f32 v[68:69], v[64:65], v[64:65]
	v_mul_f32_e32 v74, 0xbfb8aa3b, v72
	v_mul_f32_e32 v75, 0xbfb8aa3b, v73
	v_exp_f32_e32 v74, v74
	v_exp_f32_e32 v75, v75
	s_nop 0
	v_pk_add_f32 v[74:75], v[74:75], 1.0 op_sel_hi:[1,0]
	s_nop 0
	v_div_scale_f32 v99, s[0:1], v75, v75, 1.0
	v_rcp_f32_e32 v100, v99
	s_nop 0
; __device__ __forceinline__ float bf2f(bf16 v) { return __uint_as_float(((unsigned)v) << 16); }
; __device__ __forceinline__ float siluf_(float x) { return x * sigmoidf_(x); }
; __device__ __forceinline__ unsigned cvt2(float lo, float hi) { f32x2 v = {lo, hi}; return __builtin_bit_cast(unsigned, __builtin_convertvector(v, bf16x2_t)); }
; template <int STRIP> __device__ __forceinline__ void ph_gdn_prep_fast(const bf16* __restrict__ proj, const float* __restrict__ small, const float* __restrict__ conv_w, const float* __restrict__ a_log, const float* __restrict__ dt_bias, ...
;     ...
;                 for (int which = 0; which < 3; ++which) {
;                     float xf[7][4];
; #pragma unroll
;                     for (int r = 0; r < 7; ++r) { xf[r][0] = bf2f((bf16)(xr[which][r].x & 0xffff)); xf[r][1] = bf2f((bf16)(xr[which][r].x >> 16)); xf[r][2] = bf2f((bf16)(xr[which][r].y & 0xffff)); xf[r][3] = bf2f((bf16)(xr[which][r].y >> 16)); }
; #pragma unroll
;                     for (int j = 0; j < 4; ++j) { float y[4]; float ss = 0.f;
; #pragma unroll
;                         for (int e = 0; e < 4; ++e) { float v = cw[which][0][e] * xf[j][e]; v += cw[which][1][e] * xf[j + 1][e]; v += cw[which][2][e] * xf[j + 2][e]; v += cw[which][3][e] * xf[j + 3][e]; y[e] = siluf_(v); ss += y[e] * y[e]; }
;                         float r = 1.f;
;                         if (which < 2) { ss = row16_sum(ss); ss += __shfl_xor(ss, 16); r = rsqrtf(ss + NORM_EPS); if (which == 0) r *= 0.08838834764831845f; }
;                         u32x2 o; o.x = cvt2(y[0] * r, y[1] * r); o.y = cvt2(y[2] * r, y[3] * r);
;                         *(u32x2*)(L + which * (64 * GP_STR * 2) + ((4 * ts + j) * GP_STR + 4 * cg) * 2) = o; }
	v_fma_f32 v101, -v99, v100, 1.0
	v_fmac_f32_e32 v100, v101, v100
	v_div_scale_f32 v101, vcc, 1.0, v75, 1.0
	v_mul_f32_e32 v102, v101, v100
	v_fma_f32 v103, -v99, v102, v101
	v_fmac_f32_e32 v102, v103, v100
	v_fma_f32 v99, -v99, v102, v101
	v_div_fmas_f32 v99, v99, v100, v102
	v_div_fixup_f32 v75, v99, v75, 1.0
	v_div_scale_f32 v99, s[0:1], v74, v74, 1.0
	v_rcp_f32_e32 v100, v99
	s_nop 0
	v_fma_f32 v101, -v99, v100, 1.0
	v_fmac_f32_e32 v100, v101, v100
	v_div_scale_f32 v101, vcc, 1.0, v74, 1.0
	v_mul_f32_e32 v102, v101, v100
	v_fma_f32 v103, -v99, v102, v101
	v_fmac_f32_e32 v102, v103, v100
	v_fma_f32 v99, -v99, v102, v101
	v_div_fmas_f32 v99, v99, v100, v102
	v_div_fixup_f32 v74, v99, v74, 1.0
	v_pk_mul_f32 v[72:73], v[72:73], v[74:75]
	v_mov_b32_e32 v101, v76
	v_pk_mul_f32 v[74:75], v[72:73], v[72:73]
	s_nop 0
	v_mov_b32_e32 v100, v74
	v_mov_b32_e32 v76, v75
	v_pk_add_f32 v[74:75], v[100:101], v[76:77]
	v_mov_b32_e32 v76, v68
	v_mov_b32_e32 v77, v70
	v_pk_add_f32 v[74:75], v[76:77], v[74:75]
	v_mov_b32_e32 v70, v69
	v_pk_add_f32 v[68:69], v[70:71], v[74:75]
	v_mov_b32_e32 v71, v3
	v_mov_b32_e32 v70, v3
	v_and_b32_e32 v77, 0xffff0000, v94
	v_mov_b32_dpp v71, v69 row_ror:8 row_mask:0xf bank_mask:0xf
	v_mov_b32_dpp v70, v68 row_ror:8 row_mask:0xf bank_mask:0xf
	v_pk_add_f32 v[68:69], v[68:69], v[70:71]
	v_mov_b32_e32 v71, v3
	v_mov_b32_e32 v70, v3
	s_nop 0
	v_mov_b32_dpp v71, v69 row_ror:4 row_mask:0xf bank_mask:0xf
	v_mov_b32_dpp v70, v68 row_ror:4 row_mask:0xf bank_mask:0xf
	v_pk_add_f32 v[68:69], v[68:69], v[70:71]
	v_mov_b32_e32 v71, v3
	v_mov_b32_e32 v70, v3
	s_nop 0
	v_mov_b32_dpp v71, v69 row_ror:2 row_mask:0xf bank_mask:0xf
	v_mov_b32_dpp v70, v68 row_ror:2 row_mask:0xf bank_mask:0xf
	v_pk_add_f32 v[68:69], v[68:69], v[70:71]
	v_mov_b32_e32 v71, v3
	v_mov_b32_e32 v70, v3
	s_nop 0
	v_mov_b32_dpp v71, v69 row_ror:1 row_mask:0xf bank_mask:0xf
	v_mov_b32_dpp v70, v68 row_ror:1 row_mask:0xf bank_mask:0xf
	v_pk_add_f32 v[68:69], v[68:69], v[70:71]
	ds_bpermute_b32 v71, v81, v69
	ds_bpermute_b32 v70, v81, v68
	s_waitcnt lgkmcnt(0)
	v_pk_add_f32 v[68:69], v[68:69], v[70:71]
	s_nop 0
	v_pk_add_f32 v[68:69], v[68:69], s[82:83] op_sel_hi:[1,0]
	s_nop 0
	v_mul_f32_e32 v70, 0x4b800000, v69
	v_cmp_gt_f32_e64 s[0:1], s22, v69
	v_cmp_gt_f32_e32 vcc, s22, v68
	s_nop 0
	v_cndmask_b32_e64 v69, v69, v70, s[0:1]
	v_rsq_f32_e32 v69, v69
	s_nop 0
	v_mul_f32_e32 v70, 0x45800000, v69
	v_cndmask_b32_e64 v70, v69, v70, s[0:1]
	v_pk_mul_f32 v[66:67], v[66:67], v[70:71] op_sel_hi:[1,0]
	v_pk_mul_f32 v[62:63], v[62:63], v[70:71] op_sel_hi:[1,0]
	v_cvt_pk_bf16_f32 v66, v66, v67
	v_cvt_pk_bf16_f32 v67, v62, v63
	v_mul_f32_e32 v62, 0x4b800000, v68
	v_cndmask_b32_e32 v62, v68, v62, vcc
	v_rsq_f32_e32 v62, v62
	ds_write_b64 v87, v[66:67] offset:17952
	v_and_b32_e32 v69, 0xffff0000, v97
	v_lshlrev_b32_e32 v68, 16, v97
	v_mul_f32_e32 v63, 0x45800000, v62
	v_cndmask_b32_e32 v62, v62, v63, vcc
	v_pk_mul_f32 v[66:67], v[72:73], v[62:63] op_sel_hi:[1,0]
	v_pk_mul_f32 v[62:63], v[64:65], v[62:63] op_sel_hi:[1,0]
	v_cvt_pk_bf16_f32 v66, v66, v67
	v_cvt_pk_bf16_f32 v67, v62, v63
	ds_write_b64 v2, v[66:67] offset:17408
	v_and_b32_e32 v67, 0xffff0000, v96
	v_lshlrev_b32_e32 v66, 16, v96
	v_and_b32_e32 v65, 0xffff0000, v95
	v_lshlrev_b32_e32 v64, 16, v95
	v_pk_mul_f32 v[70:71], v[34:35], v[66:67]
	v_and_b32_e32 v63, 0xffff0000, v98
	v_lshlrev_b32_e32 v62, 16, v98
	v_pk_fma_f32 v[64:65], v[46:47], v[64:65], v[70:71]
	s_nop 0
	v_pk_fma_f32 v[64:65], v[42:43], v[62:63], v[64:65]
	s_nop 0
	v_pk_fma_f32 v[64:65], v[50:51], v[68:69], v[64:65]
	s_nop 0
	v_mul_f32_e32 v70, 0xbfb8aa3b, v65
	v_exp_f32_e32 v71, v70
	v_mul_f32_e32 v70, 0xbfb8aa3b, v64
	v_exp_f32_e32 v70, v70
	s_nop 0
	v_pk_add_f32 v[70:71], v[70:71], 1.0 op_sel_hi:[1,0]
	s_nop 0
	v_div_scale_f32 v72, s[0:1], v71, v71, 1.0
	v_rcp_f32_e32 v73, v72
	s_nop 0
	v_fma_f32 v74, -v72, v73, 1.0
	v_fmac_f32_e32 v73, v74, v73
	v_div_scale_f32 v74, vcc, 1.0, v71, 1.0
	v_mul_f32_e32 v75, v74, v73
	v_fma_f32 v76, -v72, v75, v74
	v_fmac_f32_e32 v75, v76, v73
	v_fma_f32 v72, -v72, v75, v74
	v_div_fmas_f32 v72, v72, v73, v75
	v_div_fixup_f32 v71, v72, v71, 1.0
	v_div_scale_f32 v72, s[0:1], v70, v70, 1.0
	v_rcp_f32_e32 v73, v72
	s_nop 0
	v_fma_f32 v74, -v72, v73, 1.0
	v_fmac_f32_e32 v73, v74, v73
	v_div_scale_f32 v74, vcc, 1.0, v70, 1.0
	v_mul_f32_e32 v75, v74, v73
	v_fma_f32 v76, -v72, v75, v74
	v_fmac_f32_e32 v75, v76, v73
	v_fma_f32 v72, -v72, v75, v74
	v_div_fmas_f32 v72, v72, v73, v75
	v_and_b32_e32 v75, 0xffff0000, v89
	v_lshlrev_b32_e32 v74, 16, v89
	v_div_fixup_f32 v70, v72, v70, 1.0
	v_and_b32_e32 v73, 0xffff0000, v88
	v_lshlrev_b32_e32 v72, 16, v88
	v_pk_mul_f32 v[88:89], v[32:33], v[74:75]
	v_lshlrev_b32_e32 v76, 16, v94
	v_pk_fma_f32 v[72:73], v[44:45], v[72:73], v[88:89]
	v_pk_mul_f32 v[70:71], v[64:65], v[70:71]
	v_and_b32_e32 v65, 0xffff0000, v91
	v_lshlrev_b32_e32 v64, 16, v91
	v_pk_fma_f32 v[72:73], v[40:41], v[76:77], v[72:73]
	s_nop 0
	v_pk_fma_f32 v[72:73], v[48:49], v[64:65], v[72:73]
	s_nop 0
	v_mul_f32_e32 v88, 0xbfb8aa3b, v73
	v_exp_f32_e32 v89, v88
	v_mul_f32_e32 v88, 0xbfb8aa3b, v72
	v_exp_f32_e32 v88, v88
	s_nop 0
	v_pk_add_f32 v[88:89], v[88:89], 1.0 op_sel_hi:[1,0]
	s_nop 0
	v_div_scale_f32 v91, s[0:1], v89, v89, 1.0
	v_rcp_f32_e32 v94, v91
	s_nop 0
	v_fma_f32 v95, -v91, v94, 1.0
	v_fmac_f32_e32 v94, v95, v94
	v_div_scale_f32 v95, vcc, 1.0, v89, 1.0
	v_mul_f32_e32 v96, v95, v94
	v_fma_f32 v97, -v91, v96, v95
	v_fmac_f32_e32 v96, v97, v94
	v_fma_f32 v91, -v91, v96, v95
	v_div_fmas_f32 v91, v91, v94, v96
	v_div_fixup_f32 v89, v91, v89, 1.0
	v_div_scale_f32 v91, s[0:1], v88, v88, 1.0
	v_rcp_f32_e32 v94, v91
; __device__ __forceinline__ float bf2f(bf16 v) { return __uint_as_float(((unsigned)v) << 16); }
; __device__ __forceinline__ float siluf_(float x) { return x * sigmoidf_(x); }
; __device__ __forceinline__ unsigned cvt2(float lo, float hi) { f32x2 v = {lo, hi}; return __builtin_bit_cast(unsigned, __builtin_convertvector(v, bf16x2_t)); }
; template <int STRIP> __device__ __forceinline__ void ph_gdn_prep_fast(const bf16* __restrict__ proj, const float* __restrict__ small, const float* __restrict__ conv_w, const float* __restrict__ a_log, const float* __restrict__ dt_bias, ...
;     ...
;                 for (int which = 0; which < 3; ++which) {
;                     float xf[7][4];
; #pragma unroll
;                     for (int r = 0; r < 7; ++r) { xf[r][0] = bf2f((bf16)(xr[which][r].x & 0xffff)); xf[r][1] = bf2f((bf16)(xr[which][r].x >> 16)); xf[r][2] = bf2f((bf16)(xr[which][r].y & 0xffff)); xf[r][3] = bf2f((bf16)(xr[which][r].y >> 16)); }
; #pragma unroll
;                     for (int j = 0; j < 4; ++j) { float y[4]; float ss = 0.f;
; #pragma unroll
;                         for (int e = 0; e < 4; ++e) { float v = cw[which][0][e] * xf[j][e]; v += cw[which][1][e] * xf[j + 1][e]; v += cw[which][2][e] * xf[j + 2][e]; v += cw[which][3][e] * xf[j + 3][e]; y[e] = siluf_(v); ss += y[e] * y[e]; }
;                         float r = 1.f;
;                         if (which < 2) { ss = row16_sum(ss); ss += __shfl_xor(ss, 16); r = rsqrtf(ss + NORM_EPS); if (which == 0) r *= 0.08838834764831845f; }
;                         u32x2 o; o.x = cvt2(y[0] * r, y[1] * r); o.y = cvt2(y[2] * r, y[3] * r);
;                         *(u32x2*)(L + which * (64 * GP_STR * 2) + ((4 * ts + j) * GP_STR + 4 * cg) * 2) = o; }
	s_nop 0
	v_fma_f32 v95, -v91, v94, 1.0
	v_fmac_f32_e32 v94, v95, v94
	v_div_scale_f32 v95, vcc, 1.0, v88, 1.0
	v_mul_f32_e32 v96, v95, v94
	v_fma_f32 v97, -v91, v96, v95
	v_fmac_f32_e32 v96, v97, v94
	v_fma_f32 v91, -v91, v96, v95
	v_div_fmas_f32 v91, v91, v94, v96
	v_div_fixup_f32 v88, v91, v88, 1.0
	v_pk_mul_f32 v[72:73], v[72:73], v[88:89]
	v_pk_mul_f32 v[88:89], v[34:35], v[62:63]
	v_cvt_pk_bf16_f32 v72, v72, v73
	v_pk_fma_f32 v[66:67], v[46:47], v[66:67], v[88:89]
	v_cvt_pk_bf16_f32 v73, v70, v71
	v_and_b32_e32 v71, 0xffff0000, v93
	v_lshlrev_b32_e32 v70, 16, v93
	v_pk_fma_f32 v[66:67], v[42:43], v[68:69], v[66:67]
	s_nop 0
	v_pk_fma_f32 v[66:67], v[50:51], v[70:71], v[66:67]
	s_nop 0
	v_mul_f32_e32 v88, 0xbfb8aa3b, v67
	v_exp_f32_e32 v89, v88
	v_mul_f32_e32 v88, 0xbfb8aa3b, v66
	v_exp_f32_e32 v88, v88
	s_nop 0
	v_pk_add_f32 v[88:89], v[88:89], 1.0 op_sel_hi:[1,0]
	s_nop 0
	v_div_scale_f32 v91, s[0:1], v89, v89, 1.0
	v_rcp_f32_e32 v93, v91
	s_nop 0
	v_fma_f32 v94, -v91, v93, 1.0
	v_fmac_f32_e32 v93, v94, v93
	v_div_scale_f32 v94, vcc, 1.0, v89, 1.0
	v_mul_f32_e32 v95, v94, v93
	v_fma_f32 v96, -v91, v95, v94
	v_fmac_f32_e32 v95, v96, v93
	v_fma_f32 v91, -v91, v95, v94
	v_div_fmas_f32 v91, v91, v93, v95
	v_div_fixup_f32 v89, v91, v89, 1.0
	v_div_scale_f32 v91, s[0:1], v88, v88, 1.0
	v_rcp_f32_e32 v93, v91
	s_nop 0
	v_fma_f32 v94, -v91, v93, 1.0
	v_fmac_f32_e32 v93, v94, v93
	v_div_scale_f32 v94, vcc, 1.0, v88, 1.0
	v_mul_f32_e32 v95, v94, v93
	v_fma_f32 v96, -v91, v95, v94
	v_fmac_f32_e32 v95, v96, v93
	v_fma_f32 v91, -v91, v95, v94
	v_div_fmas_f32 v91, v91, v93, v95
	v_div_fixup_f32 v88, v91, v88, 1.0
	v_pk_mul_f32 v[88:89], v[66:67], v[88:89]
	v_and_b32_e32 v67, 0xffff0000, v92
	v_lshlrev_b32_e32 v66, 16, v92
	v_pk_mul_f32 v[92:93], v[32:33], v[76:77]
	s_nop 0
	v_pk_fma_f32 v[74:75], v[44:45], v[74:75], v[92:93]
	s_nop 0
	v_pk_fma_f32 v[74:75], v[40:41], v[64:65], v[74:75]
	s_nop 0
	v_pk_fma_f32 v[74:75], v[48:49], v[66:67], v[74:75]
	s_nop 0
	v_mul_f32_e32 v91, 0xbfb8aa3b, v75
	v_exp_f32_e32 v93, v91
	v_mul_f32_e32 v91, 0xbfb8aa3b, v74
	v_exp_f32_e32 v92, v91
	s_nop 0
	v_pk_add_f32 v[92:93], v[92:93], 1.0 op_sel_hi:[1,0]
	s_nop 0
	v_div_scale_f32 v91, s[0:1], v93, v93, 1.0
	v_rcp_f32_e32 v94, v91
	s_nop 0
	v_fma_f32 v95, -v91, v94, 1.0
	v_fmac_f32_e32 v94, v95, v94
	v_div_scale_f32 v95, vcc, 1.0, v93, 1.0
	v_mul_f32_e32 v96, v95, v94
	v_fma_f32 v97, -v91, v96, v95
	v_fmac_f32_e32 v96, v97, v94
	v_fma_f32 v91, -v91, v96, v95
	v_div_fmas_f32 v91, v91, v94, v96
	v_div_fixup_f32 v93, v91, v93, 1.0
	v_div_scale_f32 v91, s[0:1], v92, v92, 1.0
	v_rcp_f32_e32 v94, v91
	s_nop 0
	v_fma_f32 v95, -v91, v94, 1.0
	v_fmac_f32_e32 v94, v95, v94
	v_div_scale_f32 v95, vcc, 1.0, v92, 1.0
	v_mul_f32_e32 v96, v95, v94
	v_fma_f32 v97, -v91, v96, v95
	v_fmac_f32_e32 v96, v97, v94
	v_fma_f32 v91, -v91, v96, v95
	v_div_fmas_f32 v91, v91, v94, v96
	v_div_fixup_f32 v92, v91, v92, 1.0
	v_pk_mul_f32 v[74:75], v[74:75], v[92:93]
	s_nop 0
	v_cvt_pk_bf16_f32 v74, v74, v75
	v_cvt_pk_bf16_f32 v75, v88, v89
	v_add_u32_e32 v88, 0x8800, v87
	ds_write2_b64 v88, v[72:73], v[74:75] offset1:34
	v_pk_mul_f32 v[74:75], v[34:35], v[68:69]
	v_and_b32_e32 v73, 0xffff0000, v90
	v_pk_fma_f32 v[62:63], v[46:47], v[62:63], v[74:75]
	v_lshlrev_b32_e32 v72, 16, v90
	v_pk_fma_f32 v[62:63], v[42:43], v[70:71], v[62:63]
	v_pk_mul_f32 v[70:71], v[34:35], v[70:71]
	v_pk_fma_f32 v[62:63], v[50:51], v[72:73], v[62:63]
	v_pk_fma_f32 v[68:69], v[46:47], v[68:69], v[70:71]
	v_mul_f32_e32 v74, 0xbfb8aa3b, v63
	v_exp_f32_e32 v75, v74
	v_mul_f32_e32 v74, 0xbfb8aa3b, v62
	v_exp_f32_e32 v74, v74
	v_pk_fma_f32 v[68:69], v[42:43], v[72:73], v[68:69]
	v_pk_add_f32 v[74:75], v[74:75], 1.0 op_sel_hi:[1,0]
	s_nop 0
	v_div_scale_f32 v88, s[0:1], v75, v75, 1.0
	v_rcp_f32_e32 v89, v88
	s_nop 0
	v_fma_f32 v90, -v88, v89, 1.0
	v_fmac_f32_e32 v89, v90, v89
	v_div_scale_f32 v90, vcc, 1.0, v75, 1.0
	v_mul_f32_e32 v91, v90, v89
	v_fma_f32 v92, -v88, v91, v90
	v_fmac_f32_e32 v91, v92, v89
	v_fma_f32 v88, -v88, v91, v90
	v_div_fmas_f32 v88, v88, v89, v91
	v_div_fixup_f32 v75, v88, v75, 1.0
	v_div_scale_f32 v88, s[0:1], v74, v74, 1.0
	v_rcp_f32_e32 v89, v88
	s_nop 0
	v_fma_f32 v90, -v88, v89, 1.0
	v_fmac_f32_e32 v89, v90, v89
	v_div_scale_f32 v90, vcc, 1.0, v74, 1.0
	v_mul_f32_e32 v91, v90, v89
	v_fma_f32 v92, -v88, v91, v90
	v_fmac_f32_e32 v91, v92, v89
	v_fma_f32 v88, -v88, v91, v90
	v_div_fmas_f32 v88, v88, v89, v91
	v_div_fixup_f32 v74, v88, v74, 1.0
	v_pk_mul_f32 v[88:89], v[32:33], v[64:65]
	v_pk_mul_f32 v[62:63], v[62:63], v[74:75]
	v_pk_fma_f32 v[76:77], v[44:45], v[76:77], v[88:89]
	v_and_b32_e32 v75, 0xffff0000, v86
	v_lshlrev_b32_e32 v74, 16, v86
	v_pk_fma_f32 v[76:77], v[40:41], v[66:67], v[76:77]
	v_pk_mul_f32 v[66:67], v[32:33], v[66:67]
	v_pk_fma_f32 v[76:77], v[48:49], v[74:75], v[76:77]
	v_pk_fma_f32 v[64:65], v[44:45], v[64:65], v[66:67]
	v_mul_f32_e32 v86, 0xbfb8aa3b, v77
	v_exp_f32_e32 v89, v86
; __device__ __forceinline__ float bf2f(bf16 v) { return __uint_as_float(((unsigned)v) << 16); }
; __device__ __forceinline__ float sigmoidf_(float x) { return 1.0f / (1.0f + __expf(-x)); }
; __device__ __forceinline__ float siluf_(float x) { return x * sigmoidf_(x); }
; __device__ __forceinline__ float softplusf_(float x) { const float e = __expf(-fabsf(x)); const float lp = e < 0.01f ? e * (1.f - e * (0.5f - e * 0.33333334f)) : __logf(1.f + e); return fmaxf(x, 0.f) + lp; }
; template <int STRIP> __device__ __forceinline__ void ph_gdn_prep_fast(const bf16* __restrict__ proj, const float* __restrict__ small, const float* __restrict__ conv_w, const float* __restrict__ a_log, const float* __restrict__ dt_bias, ...
;     ...
;                 for (int which = 0; which < 3; ++which) {
;                     float xf[7][4];
; #pragma unroll
;                     for (int r = 0; r < 7; ++r) { xf[r][0] = bf2f((bf16)(xr[which][r].x & 0xffff)); xf[r][1] = bf2f((bf16)(xr[which][r].x >> 16)); xf[r][2] = bf2f((bf16)(xr[which][r].y & 0xffff)); xf[r][3] = bf2f((bf16)(xr[which][r].y >> 16)); }
; #pragma unroll
;                     for (int j = 0; j < 4; ++j) { float y[4]; float ss = 0.f;
; #pragma unroll
;                         for (int e = 0; e < 4; ++e) { float v = cw[which][0][e] * xf[j][e]; v += cw[which][1][e] * xf[j + 1][e]; v += cw[which][2][e] * xf[j + 2][e]; v += cw[which][3][e] * xf[j + 3][e]; y[e] = siluf_(v); ss += y[e] * y[e]; }
;                         float r = 1.f;
;                         if (which < 2) { ss = row16_sum(ss); ss += __shfl_xor(ss, 16); r = rsqrtf(ss + NORM_EPS); if (which == 0) r *= 0.08838834764831845f; }
;                         u32x2 o; o.x = cvt2(y[0] * r, y[1] * r); o.y = cvt2(y[2] * r, y[3] * r);
;                         *(u32x2*)(L + which * (64 * GP_STR * 2) + ((4 * ts + j) * GP_STR + 4 * cg) * 2) = o; }
;                 }
;             }
;         }
;         if (wave < 2) {
;             const int cs = wave, n = 2 * (pair & 31) + cs, ci = 2 * pair + cs; const size_t m = (size_t)b * SEQ + n * 64 + lane;
;             float* sgc = (float*)(lds_dyn + cs * GP_CHUNK + GP_SC);
;             const float beta = sigmoidf_(small[m * 32 + SM_BA + h]);
;             float g = -__expf(a_log[h]) * softplusf_(small[m * 32 + SM_AA + h] + dt_bias[h]);
	v_mul_f32_e32 v86, 0xbfb8aa3b, v76
	v_exp_f32_e32 v88, v86
	v_pk_fma_f32 v[64:65], v[40:41], v[74:75], v[64:65]
	v_pk_add_f32 v[88:89], v[88:89], 1.0 op_sel_hi:[1,0]
	s_nop 0
	v_div_scale_f32 v86, s[0:1], v89, v89, 1.0
	v_rcp_f32_e32 v90, v86
	s_nop 0
	v_fma_f32 v91, -v86, v90, 1.0
	v_fmac_f32_e32 v90, v91, v90
	v_div_scale_f32 v91, vcc, 1.0, v89, 1.0
	v_mul_f32_e32 v92, v91, v90
	v_fma_f32 v93, -v86, v92, v91
	v_fmac_f32_e32 v92, v93, v90
	v_fma_f32 v86, -v86, v92, v91
	v_div_fmas_f32 v86, v86, v90, v92
	v_div_fixup_f32 v89, v86, v89, 1.0
	v_div_scale_f32 v86, s[0:1], v88, v88, 1.0
	v_rcp_f32_e32 v90, v86
	s_nop 0
	v_fma_f32 v91, -v86, v90, 1.0
	v_fmac_f32_e32 v90, v91, v90
	v_div_scale_f32 v91, vcc, 1.0, v88, 1.0
	v_mul_f32_e32 v92, v91, v90
	v_fma_f32 v93, -v86, v92, v91
	v_fmac_f32_e32 v92, v93, v90
	v_fma_f32 v86, -v86, v92, v91
	v_div_fmas_f32 v86, v86, v90, v92
	v_div_fixup_f32 v88, v86, v88, 1.0
	v_pk_mul_f32 v[76:77], v[76:77], v[88:89]
	s_nop 0
	v_cvt_pk_bf16_f32 v76, v76, v77
	v_cvt_pk_bf16_f32 v77, v62, v63
	v_and_b32_e32 v63, 0xffff0000, v85
	v_lshlrev_b32_e32 v62, 16, v85
	v_pk_fma_f32 v[62:63], v[50:51], v[62:63], v[68:69]
	ds_write_b64 v87, v[76:77] offset:35360
	v_mul_f32_e32 v68, 0xbfb8aa3b, v63
	v_exp_f32_e32 v69, v68
	v_mul_f32_e32 v68, 0xbfb8aa3b, v62
	v_exp_f32_e32 v68, v68
	s_nop 0
	v_pk_add_f32 v[68:69], v[68:69], 1.0 op_sel_hi:[1,0]
	s_nop 0
	v_div_scale_f32 v70, s[0:1], v69, v69, 1.0
	v_rcp_f32_e32 v71, v70
	s_nop 0
	v_fma_f32 v72, -v70, v71, 1.0
	v_fmac_f32_e32 v71, v72, v71
	v_div_scale_f32 v72, vcc, 1.0, v69, 1.0
	v_mul_f32_e32 v73, v72, v71
	v_fma_f32 v76, -v70, v73, v72
	v_fmac_f32_e32 v73, v76, v71
	v_fma_f32 v70, -v70, v73, v72
	v_div_fmas_f32 v70, v70, v71, v73
	v_div_fixup_f32 v69, v70, v69, 1.0
	v_div_scale_f32 v70, s[0:1], v68, v68, 1.0
	v_rcp_f32_e32 v71, v70
	s_nop 0
	v_fma_f32 v72, -v70, v71, 1.0
	v_fmac_f32_e32 v71, v72, v71
	v_div_scale_f32 v72, vcc, 1.0, v68, 1.0
	v_mul_f32_e32 v73, v72, v71
	v_fma_f32 v76, -v70, v73, v72
	v_fmac_f32_e32 v73, v76, v71
	v_fma_f32 v70, -v70, v73, v72
	v_div_fmas_f32 v70, v70, v71, v73
	v_div_fixup_f32 v68, v70, v68, 1.0
	v_pk_mul_f32 v[62:63], v[62:63], v[68:69]
	v_and_b32_e32 v69, 0xffff0000, v84
	v_lshlrev_b32_e32 v68, 16, v84
	v_pk_fma_f32 v[64:65], v[48:49], v[68:69], v[64:65]
	s_nop 0
	v_mul_f32_e32 v66, 0xbfb8aa3b, v65
	v_exp_f32_e32 v67, v66
	v_mul_f32_e32 v66, 0xbfb8aa3b, v64
	v_exp_f32_e32 v66, v66
	s_nop 0
	v_pk_add_f32 v[66:67], v[66:67], 1.0 op_sel_hi:[1,0]
	s_nop 0
	v_div_scale_f32 v68, s[0:1], v67, v67, 1.0
	v_rcp_f32_e32 v69, v68
	s_nop 0
	v_fma_f32 v70, -v68, v69, 1.0
	v_fmac_f32_e32 v69, v70, v69
	v_div_scale_f32 v70, vcc, 1.0, v67, 1.0
	v_mul_f32_e32 v71, v70, v69
	v_fma_f32 v72, -v68, v71, v70
	v_fmac_f32_e32 v71, v72, v69
	v_fma_f32 v68, -v68, v71, v70
	v_div_fmas_f32 v68, v68, v69, v71
	v_div_fixup_f32 v67, v68, v67, 1.0
	v_div_scale_f32 v68, s[0:1], v66, v66, 1.0
	v_rcp_f32_e32 v69, v68
	s_mov_b64 s[0:1], 0
	v_fma_f32 v70, -v68, v69, 1.0
	v_fmac_f32_e32 v69, v70, v69
	v_div_scale_f32 v70, vcc, 1.0, v66, 1.0
	v_mul_f32_e32 v71, v70, v69
	v_fma_f32 v72, -v68, v71, v70
	v_fmac_f32_e32 v71, v72, v69
	v_fma_f32 v68, -v68, v71, v70
	v_div_fmas_f32 v68, v68, v69, v71
	v_div_fixup_f32 v66, v68, v66, 1.0
	v_pk_mul_f32 v[64:65], v[64:65], v[66:67]
	s_and_b64 vcc, exec, s[4:5]
	v_cvt_pk_bf16_f32 v64, v64, v65
	v_cvt_pk_bf16_f32 v65, v62, v63
	ds_write_b64 v2, v[64:65] offset:34816
	s_cbranch_vccz .LBB0_1256
	v_ashrrev_i32_e32 v9, 6, v78
	v_and_b32_e32 v2, 63, v78
	v_cmp_gt_i32_e32 vcc, 2, v9
	s_and_saveexec_b64 s[4:5], vcc
	s_cbranch_execz .LBB0_1264
	v_add_lshl_u32 v4, v53, v9, 6
	v_ashrrev_i32_e32 v5, 31, v4
	v_lshl_add_u64 v[4:5], v[54:55], 0, v[4:5]
	v_or_b32_e32 v4, v4, v2
	v_ashrrev_i32_e32 v53, 31, v52
	v_lshlrev_b64 v[4:5], 7, v[4:5]
	v_lshlrev_b64 v[10:11], 2, v[52:53]
	v_lshl_add_u64 v[4:5], s[94:95], 0, v[4:5]
	v_lshl_add_u64 v[6:7], s[44:45], 0, v[10:11]
	v_lshl_add_u64 v[4:5], v[4:5], 0, v[10:11]
	global_load_dword v6, v[6:7], off
	s_nop 0
	global_load_dword v8, v[4:5], off offset:24
	global_load_dword v7, v[4:5], off
	v_lshl_add_u64 v[4:5], s[62:63], 0, v[10:11]
	global_load_dword v4, v[4:5], off
	s_mov_b32 s0, 0xbfb8aa3b
	s_waitcnt vmcnt(2)
	v_add_f32_e32 v5, v8, v6
	v_mul_f32_e64 v6, |v5|, s0
	v_exp_f32_e32 v8, v6
	s_mov_b32 s0, 0x3c23d70a
	v_cmp_ngt_f32_e32 vcc, s0, v8
	s_and_saveexec_b64 s[0:1], vcc
	s_xor_b64 s[6:7], exec, s[0:1]
	s_cbranch_execz .LBB0_1260
	v_add_f32_e32 v6, 1.0, v8
	v_cmp_gt_f32_e32 vcc, s22, v6
	s_mov_b32 s0, 0x3f317217
	s_nop 0
	v_cndmask_b32_e64 v8, 0, 32, vcc
	v_ldexp_f32 v6, v6, v8
	v_log_f32_e32 v6, v6
	s_nop 0
	v_mul_f32_e32 v8, 0x3f317217, v6
	v_fma_f32 v8, v6, s0, -v8
	v_fmac_f32_e32 v8, 0x3377d1cf, v6
	s_mov_b32 s0, 0x7f800000
	v_fmac_f32_e32 v8, 0x3f317217, v6
	v_cmp_lt_f32_e64 s[0:1], |v6|, s0
	s_nop 1
	v_cndmask_b32_e64 v6, v6, v8, s[0:1]
	v_cndmask_b32_e32 v8, 0, v235, vcc
	v_sub_f32_e32 v6, v6, v8
